# v14 + P9 cross-unit prefetch: next unit's 24 operand loads issued before the merge phase (c), which moved to v112-v156
# speedup vs baseline: 1.0148x; 1.0007x over previous
; __device__ __forceinline__ void peer_score_unit(const Frame& F, int l, int unit) {
;     ...
;         const int cc = wave >> 2, nb = wave & 3, rl = lane & 31, h = lane >> 5;
;         const bf16_t* SK = (const bf16_t*)(ws + WS_SK) + ((size_t)((l * 8 + hd) * 2 + cc) * 128 + 32 * nb + rl) * 128 + 8 * h;
;         bf16x8 bfr[8];
; #pragma unroll
;         for (int ks = 0; ks < 8; ++ks) bfr[ks] = *(const bf16x8*)(SK + 16 * ks);
;         bf16x8 afr[2][8];
; #pragma unroll
;         for (int tb = 0; tb < 2; ++tb) { const bf16_t* QP = (const bf16_t*)(ws + WS_QP) + (size_t)(r0 + 32 * tb + rl) * D + hd * 256 + cc * 128 + 8 * h;
; #pragma unroll
;             for (int ks = 0; ks < 8; ++ks) afr[tb][ks] = *(const bf16x8*)(QP + 16 * ks); }
; template <unsigned MASK> __global__ void __launch_bounds__(NTHREADS, 2) fwd(Args A0) {
;     ...
;             { for (int u = q_block(F, cwb + 384); u < ((M / 64) * 8); u = q_block(F, cwb + 384)) { peer_score_unit(F, l, u); } }
.LBB0_2042:
	v_mov_b32_e32 v0, s87
	s_waitcnt lgkmcnt(0)
	s_barrier
	ds_read_b32 v0, v0
	s_movk_i32 s1, 0x4ff
	s_waitcnt lgkmcnt(0)
	v_cmp_lt_i32_e32 vcc, s1, v0
	v_readfirstlane_b32 s7, v0
	s_cbranch_vccnz .LBB0_2055
	s_lshl_b32 s4, s10, 5
	s_ashr_i32 s1, s10, 2
	s_lshl_b32 s54, s11, 4
	s_and_b32 s46, s4, 0x60
	s_add_i32 s54, s54, s1
	s_lshl_b32 s4, s1, 7
	s_lshl_b32 s55, s1, 6
	s_lshl_b32 s1, s46, 2
	s_add_i32 s56, s1, 0
	s_ashr_i32 s1, s0, 31
	s_ashr_i32 s5, s4, 31
	s_lshl_b64 s[0:1], s[0:1], 2
	s_add_u32 s48, s42, s0
	v_lshl_add_u32 v49, s10, 6, v48
	s_mov_b32 s47, s71
	s_addc_u32 s49, s43, s1
	s_lshl_b64 s[50:51], s[4:5], 1
	s_mov_b32 s99, -1
	s_branch .LBB0_2047

; #define LAS __attribute__((address_space(3)))
; __device__ __forceinline__ int fresh_lane() { int ln; asm volatile("v_mbcnt_lo_u32_b32 %0, -1, 0\n\tv_mbcnt_hi_u32_b32 %0, -1, %0" : "=v"(ln)); return ln; }
; __device__ __forceinline__ int q_block(const Frame& F, int cw) {
;     volatile LAS int* slot = (volatile LAS int*)(F.lds + LDS_MISC + 64);
;     __syncthreads();
;     if (F.wave == 0 && fresh_lane() == 0) *slot = (int)__hip_atomic_fetch_add(F.ctl + cw, 1u, __ATOMIC_RELAXED, __HIP_MEMORY_SCOPE_AGENT);
;     __syncthreads();
;     return *slot;
; }
; template <unsigned MASK> __global__ void __launch_bounds__(NTHREADS, 2) fwd(Args A0) {
;     ...
;             { for (int u = q_block(F, cwb + 384); u < ((M / 64) * 8); u = q_block(F, cwb + 384)) { peer_score_unit(F, l, u); } }
.LBB0_2046:
	v_mov_b32_e32 v120, s87
	s_waitcnt lgkmcnt(0)
	s_barrier
	ds_read_b32 v120, v120
	s_movk_i32 s0, 0x500
	s_waitcnt lgkmcnt(0)
	v_cmp_gt_i32_e32 vcc, s0, v120
	v_readfirstlane_b32 s7, v120
	s_cbranch_vccz .LBB0_2055

; __device__ __forceinline__ void peer_score_unit(const Frame& F, int l, int unit) {
;     ...
;     for (int repa = 0; repa < P9_REP_A; ++repa) {
;         const int cc = wave >> 2, nb = wave & 3, rl = lane & 31, h = lane >> 5;
;         const bf16_t* SK = (const bf16_t*)(ws + WS_SK) + ((size_t)((l * 8 + hd) * 2 + cc) * 128 + 32 * nb + rl) * 128 + 8 * h;
;         bf16x8 bfr[8];
; #pragma unroll
;         for (int ks = 0; ks < 8; ++ks) bfr[ks] = *(const bf16x8*)(SK + 16 * ks);
;         bf16x8 afr[2][8];
; #pragma unroll
;         for (int tb = 0; tb < 2; ++tb) { const bf16_t* QP = (const bf16_t*)(ws + WS_QP) + (size_t)(r0 + 32 * tb + rl) * D + hd * 256 + cc * 128 + 8 * h;
; #pragma unroll
;             for (int ks = 0; ks < 8; ++ks) afr[tb][ks] = *(const bf16x8*)(QP + 16 * ks); }
;         asm volatile("" : "+v"(afr[0][0]), "+v"(afr[0][1]), "+v"(afr[0][2]), "+v"(afr[0][3]), "+v"(afr[0][4]), "+v"(afr[0][5]), "+v"(afr[0][6]), "+v"(afr[0][7]),
;                      "+v"(afr[1][0]), "+v"(afr[1][1]), "+v"(afr[1][2]), "+v"(afr[1][3]), "+v"(afr[1][4]), "+v"(afr[1][5]), "+v"(afr[1][6]), "+v"(afr[1][7]));
; #pragma unroll
;         for (int tb = 0; tb < 2; ++tb) {
;             f32x16 acc;
; #pragma unroll
;             for (int i = 0; i < 16; ++i) acc[i] = 0.f;
; #pragma unroll
;             for (int ks = 0; ks < 8; ++ks) acc = __builtin_amdgcn_mfma_f32_32x32x16_bf16(afr[tb][ks], bfr[ks], acc, 0, 0, 0);
; #pragma unroll
;             for (int i = 0; i < 16; ++i) { const int t = 32 * tb + (i & 3) + 8 * (i >> 2) + 4 * h; S[(cc * 64 + t) * 129 + 32 * nb + rl] = acc[i]; }
;         }
;     }
;     __syncthreads();
.Lq_p9_top:
	s_cmp_eq_u32 s99, s7
	s_cbranch_scc1 .Lp9_top_pf
	s_and_b32 s6, s7, 7
	s_lshl_b32 s0, s6, 1
	s_add_i32 s0, s54, s0
	s_ashr_i32 s1, s0, 31
	v_mov_b32_e32 v0, v48
	v_mov_b32_e32 v50, v49
	s_lshl_b64 s[0:1], s[0:1], 7
	s_or_b64 s[0:1], s[0:1], s[46:47]
	v_and_b32_e32 v6, 31, v0
	v_ashrrev_i32_e32 v7, 5, v0
	v_or_b32_e32 v0, s0, v6
	v_mov_b32_e32 v1, s1
	v_lshlrev_b32_e32 v2, 3, v7
	s_mov_b64 s[4:5], s[42:43]
	v_lshlrev_b64 v[0:1], 8, v[0:1]
	v_ashrrev_i32_e32 v3, 31, v2
	v_lshlrev_b64 v[2:3], 1, v[2:3]
	v_lshl_add_u64 v[0:1], s[4:5], 0, v[0:1]
	v_lshl_add_u64 v[0:1], v[0:1], 0, v[2:3]
	s_mov_b64 s[0:1], 0xbc80000
	s_lshl_b32 s7, s7, 3
	v_lshl_add_u64 v[4:5], v[0:1], 0, s[0:1]
	s_lshl_b32 s0, s6, 9
	s_add_u32 s0, s4, s0
	s_addc_u32 s1, s5, 0
	s_mov_b32 s8, 0xbc80000
	s_add_u32 s0, s0, s50
	v_add_co_u32_e32 v0, vcc, s8, v0
	s_addc_u32 s1, s1, s51
	s_nop 0
	v_addc_co_u32_e32 v1, vcc, 0, v1, vcc
	s_andn2_b32 s7, s7, 63
	global_load_dwordx4 v[44:47], v[0:1], off
	global_load_dwordx4 v[40:43], v[4:5], off offset:32
	global_load_dwordx4 v[36:39], v[4:5], off offset:64
	global_load_dwordx4 v[32:35], v[4:5], off offset:96
	global_load_dwordx4 v[28:31], v[4:5], off offset:128
	global_load_dwordx4 v[16:19], v[4:5], off offset:160
	global_load_dwordx4 v[20:23], v[4:5], off offset:192
	global_load_dwordx4 v[24:27], v[4:5], off offset:224
	v_or_b32_e32 v0, s7, v6
	v_ashrrev_i32_e32 v1, 31, v0
	v_lshlrev_b64 v[4:5], 12, v[0:1]
	v_or_b32_e32 v0, 32, v0
	v_lshl_add_u64 v[2:3], s[0:1], 0, v[2:3]
	s_mov_b64 s[0:1], 0x44bd0000
	v_ashrrev_i32_e32 v1, 31, v0
	v_lshl_add_u64 v[2:3], v[2:3], 0, s[0:1]
	v_lshlrev_b64 v[0:1], 12, v[0:1]
	v_lshl_add_u64 v[0:1], v[2:3], 0, v[0:1]
	v_lshl_add_u64 v[4:5], v[2:3], 0, v[4:5]
	global_load_dwordx4 v[52:55], v[0:1], off offset:224
	global_load_dwordx4 v[56:59], v[0:1], off offset:192
	global_load_dwordx4 v[60:63], v[0:1], off offset:160
	global_load_dwordx4 v[64:67], v[0:1], off offset:128
	global_load_dwordx4 v[68:71], v[0:1], off offset:96
	global_load_dwordx4 v[72:75], v[0:1], off offset:64
	global_load_dwordx4 v[76:79], v[0:1], off offset:32
	global_load_dwordx4 v[80:83], v[0:1], off
	global_load_dwordx4 v[84:87], v[4:5], off offset:224
	global_load_dwordx4 v[88:91], v[4:5], off offset:192
	global_load_dwordx4 v[92:95], v[4:5], off offset:160
	global_load_dwordx4 v[96:99], v[4:5], off offset:128
	global_load_dwordx4 v[100:103], v[4:5], off offset:96
	global_load_dwordx4 v[104:107], v[4:5], off offset:64
	global_load_dwordx4 v[108:111], v[4:5], off offset:32
	global_load_dwordx4 v[0:3], v[4:5], off
	v_lshl_add_u32 v51, v7, 2, s55
	v_lshlrev_b32_e32 v112, 2, v6
	v_mul_lo_u32 v51, v51, s33
	v_add3_u32 v51, s56, v112, v51
.Lp9_wait:
	s_waitcnt vmcnt(0)
	s_cmp_eq_u64 s[44:45], 0
	s_cbranch_scc1 .Lp9_nw0
	v_readfirstlane_b32 s101, v150
	v_mov_b32_e32 v121, s87
	s_nop 0
	v_mov_b32_e32 v120, s101
	ds_write_b32 v121, v120 offset:8
.Lp9_nw0:
	s_nop 0
	v_mfma_f32_32x32x16_bf16 v[0:15], v[0:3], v[44:47], 0
	v_mfma_f32_32x32x16_bf16 v[0:15], v[108:111], v[40:43], v[0:15]
	v_mfma_f32_32x32x16_bf16 v[0:15], v[104:107], v[36:39], v[0:15]
	v_mfma_f32_32x32x16_bf16 v[0:15], v[100:103], v[32:35], v[0:15]
	v_mfma_f32_32x32x16_bf16 v[0:15], v[96:99], v[28:31], v[0:15]
	v_mfma_f32_32x32x16_bf16 v[0:15], v[92:95], v[16:19], v[0:15]
	v_mfma_f32_32x32x16_bf16 v[0:15], v[88:91], v[20:23], v[0:15]
	v_mfma_f32_32x32x16_bf16 v[0:15], v[84:87], v[24:27], v[0:15]
	s_nop 11
	ds_write2_b32 v51, v0, v1 offset1:129
	v_add_u32_e32 v0, 0x400, v51
	ds_write2_b32 v0, v2, v3 offset0:2 offset1:131
	v_add_u32_e32 v0, 0x1000, v51
	ds_write2_b32 v0, v4, v5 offset0:8 offset1:137
	v_add_u32_e32 v0, 0x1400, v51
	ds_write2_b32 v0, v6, v7 offset0:10 offset1:139
	v_add_u32_e32 v0, 0x2000, v51
	ds_write2_b32 v0, v8, v9 offset0:16 offset1:145
	v_add_u32_e32 v0, 0x2400, v51
	ds_write2_b32 v0, v10, v11 offset0:18 offset1:147
	v_add_u32_e32 v0, 0x3000, v51
	ds_write2_b32 v0, v12, v13 offset0:24 offset1:153
	v_add_u32_e32 v0, 0x3400, v51
	ds_write2_b32 v0, v14, v15 offset0:26 offset1:155
	v_mfma_f32_32x32x16_bf16 v[0:15], v[80:83], v[44:47], 0
	v_mfma_f32_32x32x16_bf16 v[0:15], v[76:79], v[40:43], v[0:15]
	v_mfma_f32_32x32x16_bf16 v[0:15], v[72:75], v[36:39], v[0:15]
	v_mfma_f32_32x32x16_bf16 v[0:15], v[68:71], v[32:35], v[0:15]
	v_mfma_f32_32x32x16_bf16 v[0:15], v[64:67], v[28:31], v[0:15]
	v_mfma_f32_32x32x16_bf16 v[0:15], v[60:63], v[16:19], v[0:15]
	v_add_u32_e32 v16, 0x4000, v51
	v_mfma_f32_32x32x16_bf16 v[0:15], v[56:59], v[20:23], v[0:15]
	v_mfma_f32_32x32x16_bf16 v[0:15], v[52:55], v[24:27], v[0:15]
	s_nop 11
	ds_write2_b32 v16, v0, v1 offset0:32 offset1:161
	v_add_u32_e32 v0, 0x4400, v51
	ds_write2_b32 v0, v2, v3 offset0:34 offset1:163
	v_add_u32_e32 v0, 0x5000, v51
	ds_write2_b32 v0, v4, v5 offset0:40 offset1:169
	v_add_u32_e32 v0, 0x5400, v51
	ds_write2_b32 v0, v6, v7 offset0:42 offset1:171
	v_add_u32_e32 v0, 0x6000, v51
	ds_write2_b32 v0, v8, v9 offset0:48 offset1:177
	v_add_u32_e32 v0, 0x6400, v51
	ds_write2_b32 v0, v10, v11 offset0:50 offset1:179
	v_add_u32_e32 v0, 0x7000, v51
	ds_write2_b32 v0, v12, v13 offset0:56 offset1:185
	v_add_u32_e32 v0, 0x7400, v51
	v_ashrrev_i32_e32 v1, 2, v50
	ds_write2_b32 v0, v14, v15 offset0:58 offset1:187
	v_mul_lo_u32 v0, v1, s33
	v_and_b32_e32 v4, 3, v50
	v_add_u32_e32 v0, 0, v0
	v_lshl_add_u32 v3, v4, 7, v0
	s_waitcnt lgkmcnt(0)
	s_barrier
; #define LAS __attribute__((address_space(3)))
; __device__ __forceinline__ void peer_score_unit(const Frame& F, int l, int unit) {
;     ...
;         const int row = tid >> 2, qd = tid & 3;
;         const LAS float* base = S + row * 129 + 32 * qd;
;         unsigned x[32];
; #pragma unroll
;         for (int j = 0; j < 32; ++j) { const unsigned u = __float_as_uint(base[j]); const unsigned o = (u & 0x80000000u) ? ~u : (u | 0x80000000u); x[j] = (o & ~127u) | (unsigned)(127 - (32 * qd + j)); }
	v_lshlrev_b32_e32 v2, 5, v4
	v_cmp_eq_u32_e32 vcc, 0, v4
	ds_read2_b32 v[4:5], v3 offset1:1
	s_waitcnt lgkmcnt(0)
	v_not_b32_e32 v6, v4
	v_cmp_gt_i32_e64 s[0:1], 0, v4
	s_nop 1
	v_cndmask_b32_e64 v4, -|v4|, v6, s[0:1]
	v_and_b32_e32 v4, 0xffffff80, v4
	s_movk_i32 s0, 0x7f
	v_bitop3_b32 v4, v4, s0, v2 bitop3:0x36
	v_not_b32_e32 v6, v5
	v_cmp_gt_i32_e64 s[0:1], 0, v5
	s_nop 1
	v_cndmask_b32_e64 v5, -|v5|, v6, s[0:1]
	ds_read2_b32 v[6:7], v3 offset0:2 offset1:3
	v_and_b32_e32 v5, 0xffffff80, v5
	v_sub_u32_e32 v5, v5, v2
	v_add_u32_e32 v5, 0x7e, v5
	s_waitcnt lgkmcnt(0)
	v_not_b32_e32 v8, v6
	v_cmp_gt_i32_e64 s[0:1], 0, v6
	s_nop 1
	v_cndmask_b32_e64 v6, -|v6|, v8, s[0:1]
	v_not_b32_e32 v8, v7
	v_cmp_gt_i32_e64 s[0:1], 0, v7
	v_and_b32_e32 v6, 0xffffff80, v6
	v_sub_u32_e32 v6, v6, v2
	v_cndmask_b32_e64 v7, -|v7|, v8, s[0:1]
	ds_read2_b32 v[8:9], v3 offset0:4 offset1:5
	v_and_b32_e32 v7, 0xffffff80, v7
	v_sub_u32_e32 v7, v7, v2
	v_add_u32_e32 v6, 0x7d, v6
	v_add_u32_e32 v7, 0x7c, v7
	s_waitcnt lgkmcnt(0)
	v_not_b32_e32 v10, v8
	v_cmp_gt_i32_e64 s[0:1], 0, v8
	s_nop 1
	v_cndmask_b32_e64 v8, -|v8|, v10, s[0:1]
	v_not_b32_e32 v10, v9
	v_cmp_gt_i32_e64 s[0:1], 0, v9
	v_and_b32_e32 v8, 0xffffff80, v8
	v_sub_u32_e32 v8, v8, v2
	v_cndmask_b32_e64 v9, -|v9|, v10, s[0:1]
	ds_read2_b32 v[10:11], v3 offset0:6 offset1:7
	v_and_b32_e32 v9, 0xffffff80, v9
	v_sub_u32_e32 v9, v9, v2
	v_add_u32_e32 v8, 0x7b, v8
	v_add_u32_e32 v9, 0x7a, v9
	s_waitcnt lgkmcnt(0)
	v_not_b32_e32 v12, v10
	v_cmp_gt_i32_e64 s[0:1], 0, v10
	s_nop 1
	v_cndmask_b32_e64 v10, -|v10|, v12, s[0:1]
	v_not_b32_e32 v12, v11
	v_cmp_gt_i32_e64 s[0:1], 0, v11
	v_and_b32_e32 v10, 0xffffff80, v10
	v_sub_u32_e32 v10, v10, v2
	v_cndmask_b32_e64 v11, -|v11|, v12, s[0:1]
	ds_read2_b32 v[12:13], v3 offset0:8 offset1:9
	v_and_b32_e32 v11, 0xffffff80, v11
	v_sub_u32_e32 v11, v11, v2
	v_add_u32_e32 v10, 0x79, v10
	v_add_u32_e32 v11, 0x78, v11
	s_waitcnt lgkmcnt(0)
	v_not_b32_e32 v14, v12
	v_cmp_gt_i32_e64 s[0:1], 0, v12
	s_nop 1
	v_cndmask_b32_e64 v12, -|v12|, v14, s[0:1]
	v_not_b32_e32 v14, v13
	v_cmp_gt_i32_e64 s[0:1], 0, v13
	v_and_b32_e32 v12, 0xffffff80, v12
	v_sub_u32_e32 v12, v12, v2
	v_cndmask_b32_e64 v13, -|v13|, v14, s[0:1]
	ds_read2_b32 v[14:15], v3 offset0:10 offset1:11
	v_and_b32_e32 v13, 0xffffff80, v13
	v_sub_u32_e32 v13, v13, v2
	v_add_u32_e32 v12, 0x77, v12
	v_add_u32_e32 v13, 0x76, v13
	s_waitcnt lgkmcnt(0)
	v_not_b32_e32 v16, v14
	v_cmp_gt_i32_e64 s[0:1], 0, v14
	s_nop 1
	v_cndmask_b32_e64 v14, -|v14|, v16, s[0:1]
	v_not_b32_e32 v16, v15
	v_cmp_gt_i32_e64 s[0:1], 0, v15
	v_and_b32_e32 v14, 0xffffff80, v14
	v_sub_u32_e32 v14, v14, v2
	v_cndmask_b32_e64 v15, -|v15|, v16, s[0:1]
	ds_read2_b32 v[16:17], v3 offset0:12 offset1:13
	v_and_b32_e32 v15, 0xffffff80, v15
	v_sub_u32_e32 v15, v15, v2
	v_add_u32_e32 v14, 0x75, v14
	v_add_u32_e32 v15, 0x74, v15
	s_waitcnt lgkmcnt(0)
	v_not_b32_e32 v18, v16
	v_cmp_gt_i32_e64 s[0:1], 0, v16
	s_nop 1
	v_cndmask_b32_e64 v16, -|v16|, v18, s[0:1]
	v_not_b32_e32 v18, v17
	v_cmp_gt_i32_e64 s[0:1], 0, v17
	v_and_b32_e32 v16, 0xffffff80, v16
	v_sub_u32_e32 v16, v16, v2
	v_cndmask_b32_e64 v17, -|v17|, v18, s[0:1]
	ds_read2_b32 v[18:19], v3 offset0:14 offset1:15
	v_and_b32_e32 v17, 0xffffff80, v17
	v_sub_u32_e32 v17, v17, v2
	v_add_u32_e32 v16, 0x73, v16
	v_add_u32_e32 v17, 0x72, v17
	s_waitcnt lgkmcnt(0)
	v_not_b32_e32 v20, v18
	v_cmp_gt_i32_e64 s[0:1], 0, v18
	s_nop 1
	v_cndmask_b32_e64 v18, -|v18|, v20, s[0:1]
	v_not_b32_e32 v20, v19
	v_cmp_gt_i32_e64 s[0:1], 0, v19
	v_and_b32_e32 v18, 0xffffff80, v18
	v_sub_u32_e32 v18, v18, v2
	v_cndmask_b32_e64 v19, -|v19|, v20, s[0:1]
	ds_read2_b32 v[20:21], v3 offset0:16 offset1:17
	v_and_b32_e32 v19, 0xffffff80, v19
	v_sub_u32_e32 v19, v19, v2
	v_add_u32_e32 v18, 0x71, v18
	v_add_u32_e32 v19, 0x70, v19
	s_waitcnt lgkmcnt(0)
	v_not_b32_e32 v22, v20
	v_cmp_gt_i32_e64 s[0:1], 0, v20
	s_nop 1
	v_cndmask_b32_e64 v20, -|v20|, v22, s[0:1]
	v_not_b32_e32 v22, v21
	v_cmp_gt_i32_e64 s[0:1], 0, v21
	v_and_b32_e32 v20, 0xffffff80, v20
	v_sub_u32_e32 v20, v20, v2
	v_cndmask_b32_e64 v21, -|v21|, v22, s[0:1]
	ds_read2_b32 v[22:23], v3 offset0:18 offset1:19
	v_and_b32_e32 v21, 0xffffff80, v21
	v_sub_u32_e32 v21, v21, v2
	v_add_u32_e32 v20, 0x6f, v20
	v_add_u32_e32 v21, 0x6e, v21
	s_waitcnt lgkmcnt(0)
	v_not_b32_e32 v24, v22
	v_cmp_gt_i32_e64 s[0:1], 0, v22
	s_nop 1
	v_cndmask_b32_e64 v22, -|v22|, v24, s[0:1]
	v_not_b32_e32 v24, v23
	v_cmp_gt_i32_e64 s[0:1], 0, v23
	v_and_b32_e32 v22, 0xffffff80, v22
	v_sub_u32_e32 v22, v22, v2
	v_cndmask_b32_e64 v23, -|v23|, v24, s[0:1]
	ds_read2_b32 v[24:25], v3 offset0:20 offset1:21
	v_and_b32_e32 v23, 0xffffff80, v23
	v_sub_u32_e32 v23, v23, v2
	v_add_u32_e32 v22, 0x6d, v22
	v_add_u32_e32 v23, 0x6c, v23
	s_waitcnt lgkmcnt(0)
	v_not_b32_e32 v26, v24
	v_cmp_gt_i32_e64 s[0:1], 0, v24
	s_nop 1
	v_cndmask_b32_e64 v24, -|v24|, v26, s[0:1]
	v_and_b32_e32 v24, 0xffffff80, v24
	v_sub_u32_e32 v24, v24, v2
	v_add_u32_e32 v26, 0x6b, v24
	v_not_b32_e32 v24, v25
	v_cmp_gt_i32_e64 s[0:1], 0, v25
	s_nop 1
	v_cndmask_b32_e64 v24, -|v25|, v24, s[0:1]
	v_and_b32_e32 v24, 0xffffff80, v24
	v_sub_u32_e32 v24, v24, v2
	v_add_u32_e32 v27, 0x6a, v24
	ds_read2_b32 v[24:25], v3 offset0:22 offset1:23
	s_waitcnt lgkmcnt(0)
	v_not_b32_e32 v28, v24
	v_cmp_gt_i32_e64 s[0:1], 0, v24
	s_nop 1
	v_cndmask_b32_e64 v24, -|v24|, v28, s[0:1]
	v_and_b32_e32 v24, 0xffffff80, v24
	v_sub_u32_e32 v24, v24, v2
	v_add_u32_e32 v28, 0x69, v24
	v_not_b32_e32 v24, v25
	v_cmp_gt_i32_e64 s[0:1], 0, v25
	s_nop 1
	v_cndmask_b32_e64 v24, -|v25|, v24, s[0:1]
	v_and_b32_e32 v24, 0xffffff80, v24
	v_sub_u32_e32 v24, v24, v2
	v_add_u32_e32 v29, 0x68, v24
	ds_read2_b32 v[24:25], v3 offset0:24 offset1:25
	s_waitcnt lgkmcnt(0)
; #define CE_DESC(a_, b_) do { const unsigned hi_ = max(x[a_], x[b_]), lo_ = min(x[a_], x[b_]); x[a_] = hi_; x[b_] = lo_; } while (0)
; __device__ __forceinline__ void peer_score_unit(const Frame& F, int l, int unit) {
;     ...
;         for (int j = 0; j < 32; ++j) { const unsigned u = __float_as_uint(base[j]); const unsigned o = (u & 0x80000000u) ? ~u : (u | 0x80000000u); x[j] = (o & ~127u) | (unsigned)(127 - (32 * qd + j)); }
;     ...
; #pragma unroll
;         for (int k = 2; k <= 16; k <<= 1)
; #pragma unroll
;             for (int j = k >> 1; j > 0; j >>= 1)
; #pragma unroll
;                 for (int i = 0; i < 32; ++i) { const int l2 = i ^ j; if (l2 > i) { if ((i & k) == 0) CE_DESC(i, l2); else CE_DESC(l2, i); } }
	v_not_b32_e32 v30, v24
	v_cmp_gt_i32_e64 s[0:1], 0, v24
	s_nop 1
	v_cndmask_b32_e64 v24, -|v24|, v30, s[0:1]
	v_and_b32_e32 v24, 0xffffff80, v24
	v_sub_u32_e32 v24, v24, v2
	v_add_u32_e32 v30, 0x67, v24
	v_not_b32_e32 v24, v25
	v_cmp_gt_i32_e64 s[0:1], 0, v25
	s_nop 1
	v_cndmask_b32_e64 v24, -|v25|, v24, s[0:1]
	v_and_b32_e32 v24, 0xffffff80, v24
	v_sub_u32_e32 v24, v24, v2
	v_add_u32_e32 v31, 0x66, v24
	ds_read2_b32 v[24:25], v3 offset0:26 offset1:27
	s_waitcnt lgkmcnt(0)
	v_not_b32_e32 v32, v24
	v_cmp_gt_i32_e64 s[0:1], 0, v24
	s_nop 1
	v_cndmask_b32_e64 v24, -|v24|, v32, s[0:1]
	v_and_b32_e32 v24, 0xffffff80, v24
	v_sub_u32_e32 v24, v24, v2
	v_add_u32_e32 v32, 0x65, v24
	v_not_b32_e32 v24, v25
	v_cmp_gt_i32_e64 s[0:1], 0, v25
	s_nop 1
	v_cndmask_b32_e64 v24, -|v25|, v24, s[0:1]
	v_and_b32_e32 v24, 0xffffff80, v24
	v_sub_u32_e32 v24, v24, v2
	v_add_u32_e32 v33, 0x64, v24
	ds_read2_b32 v[24:25], v3 offset0:28 offset1:29
	s_waitcnt lgkmcnt(0)
	v_not_b32_e32 v34, v24
	v_cmp_gt_i32_e64 s[0:1], 0, v24
	s_nop 1
	v_cndmask_b32_e64 v24, -|v24|, v34, s[0:1]
	v_and_b32_e32 v24, 0xffffff80, v24
	v_sub_u32_e32 v24, v24, v2
	v_add_u32_e32 v34, 0x63, v24
	v_not_b32_e32 v24, v25
	v_cmp_gt_i32_e64 s[0:1], 0, v25
	s_nop 1
	v_cndmask_b32_e64 v24, -|v25|, v24, s[0:1]
	v_and_b32_e32 v24, 0xffffff80, v24
	v_sub_u32_e32 v24, v24, v2
	v_add_u32_e32 v35, 0x62, v24
	ds_read2_b32 v[24:25], v3 offset0:30 offset1:31
	s_waitcnt lgkmcnt(0)
	v_not_b32_e32 v3, v24
	v_cmp_gt_i32_e64 s[0:1], 0, v24
	s_nop 1
	v_cndmask_b32_e64 v3, -|v24|, v3, s[0:1]
	v_not_b32_e32 v24, v25
	v_cmp_gt_i32_e64 s[0:1], 0, v25
	v_and_b32_e32 v3, 0xffffff80, v3
	v_sub_u32_e32 v3, v3, v2
	v_cndmask_b32_e64 v24, -|v25|, v24, s[0:1]
	v_and_b32_e32 v24, 0xffffff80, v24
	v_sub_u32_e32 v2, v24, v2
	v_add_u32_e32 v3, 0x61, v3
	v_add_u32_e32 v2, 0x60, v2
	v_max_u32_e32 v24, v4, v5
	v_min_u32_e32 v4, v4, v5
	v_max_u32_e32 v5, v7, v6
	v_min_u32_e32 v6, v7, v6
	v_max_u32_e32 v7, v8, v9
	v_min_u32_e32 v8, v8, v9
	v_max_u32_e32 v9, v11, v10
	v_min_u32_e32 v10, v11, v10
	v_max_u32_e32 v11, v12, v13
	v_min_u32_e32 v12, v12, v13
	v_max_u32_e32 v13, v15, v14
	v_min_u32_e32 v14, v15, v14
	v_max_u32_e32 v15, v16, v17
	v_min_u32_e32 v16, v16, v17
	v_max_u32_e32 v17, v19, v18
	v_min_u32_e32 v18, v19, v18
	v_max_u32_e32 v19, v20, v21
	v_min_u32_e32 v20, v20, v21
	v_max_u32_e32 v21, v23, v22
	v_min_u32_e32 v22, v23, v22
	v_max_u32_e32 v23, v26, v27
	v_min_u32_e32 v25, v26, v27
	v_max_u32_e32 v26, v29, v28
	v_min_u32_e32 v27, v29, v28
	v_max_u32_e32 v28, v30, v31
	v_min_u32_e32 v29, v30, v31
	v_max_u32_e32 v30, v33, v32
	v_min_u32_e32 v31, v33, v32
	v_max_u32_e32 v32, v34, v35
	v_min_u32_e32 v33, v34, v35
	v_max_u32_e32 v34, v2, v3
	v_min_u32_e32 v2, v2, v3
	v_max_u32_e32 v3, v24, v6
	v_min_u32_e32 v6, v24, v6
	v_max_u32_e32 v24, v4, v5
	v_min_u32_e32 v4, v4, v5
	v_max_u32_e32 v5, v10, v7
	v_min_u32_e32 v7, v10, v7
	v_max_u32_e32 v10, v9, v8
	v_min_u32_e32 v8, v9, v8
	v_max_u32_e32 v9, v11, v14
	v_min_u32_e32 v11, v11, v14
	v_max_u32_e32 v14, v12, v13
	v_min_u32_e32 v12, v12, v13
	v_max_u32_e32 v13, v18, v15
	v_min_u32_e32 v15, v18, v15
	v_max_u32_e32 v18, v17, v16
	v_min_u32_e32 v16, v17, v16
	v_max_u32_e32 v17, v19, v22
	v_min_u32_e32 v19, v19, v22
	v_max_u32_e32 v22, v20, v21
	v_min_u32_e32 v20, v20, v21
	v_max_u32_e32 v21, v27, v23
	v_min_u32_e32 v23, v27, v23
	v_max_u32_e32 v27, v26, v25
	v_min_u32_e32 v25, v26, v25
	v_max_u32_e32 v26, v28, v31
	v_min_u32_e32 v28, v28, v31
	v_max_u32_e32 v31, v29, v30
	v_min_u32_e32 v29, v29, v30
	v_max_u32_e32 v30, v2, v32
	v_min_u32_e32 v2, v2, v32
	v_max_u32_e32 v32, v34, v33
	v_min_u32_e32 v33, v34, v33
	v_max_u32_e32 v34, v3, v24
	v_min_u32_e32 v3, v3, v24
	v_max_u32_e32 v24, v6, v4
	v_min_u32_e32 v4, v6, v4
	v_max_u32_e32 v6, v8, v7
	v_min_u32_e32 v7, v8, v7
	v_max_u32_e32 v8, v10, v5
	v_min_u32_e32 v5, v10, v5
	v_max_u32_e32 v10, v9, v14
	v_min_u32_e32 v9, v9, v14
	v_max_u32_e32 v14, v11, v12
	v_min_u32_e32 v11, v11, v12
	v_max_u32_e32 v12, v16, v15
	v_min_u32_e32 v15, v16, v15
	v_max_u32_e32 v16, v18, v13
	v_min_u32_e32 v13, v18, v13
	v_max_u32_e32 v18, v17, v22
	v_min_u32_e32 v17, v17, v22
	v_max_u32_e32 v22, v19, v20
	v_min_u32_e32 v19, v19, v20
	v_max_u32_e32 v20, v25, v23
	v_min_u32_e32 v23, v25, v23
	v_max_u32_e32 v25, v27, v21
	v_min_u32_e32 v21, v27, v21
	v_max_u32_e32 v27, v26, v31
	v_min_u32_e32 v26, v26, v31
	v_max_u32_e32 v31, v28, v29
	v_min_u32_e32 v28, v28, v29
	v_max_u32_e32 v29, v33, v2
	v_min_u32_e32 v2, v33, v2
	v_max_u32_e32 v33, v32, v30
	v_min_u32_e32 v30, v32, v30
	v_max_u32_e32 v32, v34, v7
	v_min_u32_e32 v7, v34, v7
	v_max_u32_e32 v34, v3, v6
	v_min_u32_e32 v3, v3, v6
	v_max_u32_e32 v6, v24, v5
	v_min_u32_e32 v5, v24, v5
	v_max_u32_e32 v24, v4, v8
	v_min_u32_e32 v4, v4, v8
	v_max_u32_e32 v8, v15, v10
	v_min_u32_e32 v10, v15, v10
	v_max_u32_e32 v15, v12, v9
	v_min_u32_e32 v9, v12, v9
	v_max_u32_e32 v12, v13, v14
	v_min_u32_e32 v13, v13, v14
	v_max_u32_e32 v14, v16, v11
	v_min_u32_e32 v11, v16, v11
	v_max_u32_e32 v16, v18, v23
	v_min_u32_e32 v18, v18, v23
	v_max_u32_e32 v23, v17, v20
	v_min_u32_e32 v17, v17, v20
	v_max_u32_e32 v20, v22, v21
	v_min_u32_e32 v21, v22, v21
	v_max_u32_e32 v22, v19, v25
	v_min_u32_e32 v19, v19, v25
	v_max_u32_e32 v25, v2, v27
	v_min_u32_e32 v2, v2, v27
	v_max_u32_e32 v27, v29, v26
	v_min_u32_e32 v26, v29, v26
	v_max_u32_e32 v29, v30, v31
	v_min_u32_e32 v30, v30, v31
	v_max_u32_e32 v31, v33, v28
	v_min_u32_e32 v28, v33, v28
	v_max_u32_e32 v33, v32, v6
	v_min_u32_e32 v6, v32, v6
	v_max_u32_e32 v32, v34, v24
	v_min_u32_e32 v24, v34, v24
	v_max_u32_e32 v34, v7, v5
	v_min_u32_e32 v5, v7, v5
	v_max_u32_e32 v7, v3, v4
; #define CE_DESC(a_, b_) do { const unsigned hi_ = max(x[a_], x[b_]), lo_ = min(x[a_], x[b_]); x[a_] = hi_; x[b_] = lo_; } while (0)
; __device__ __forceinline__ void peer_score_unit(const Frame& F, int l, int unit) {
;     ...
;         for (int j = 0; j < 32; ++j) { const unsigned u = __float_as_uint(base[j]); const unsigned o = (u & 0x80000000u) ? ~u : (u | 0x80000000u); x[j] = (o & ~127u) | (unsigned)(127 - (32 * qd + j)); }
;     ...
; #pragma unroll
;         for (int k = 2; k <= 16; k <<= 1)
; #pragma unroll
;             for (int j = k >> 1; j > 0; j >>= 1)
; #pragma unroll
;                 for (int i = 0; i < 32; ++i) { const int l2 = i ^ j; if (l2 > i) { if ((i & k) == 0) CE_DESC(i, l2); else CE_DESC(l2, i); } }
; #pragma unroll
;         for (int i = 0; i < 16; ++i) x[i] = max(x[i], x[i + 16]);
; #pragma unroll
;         for (int j = 8; j > 0; j >>= 1)
; #pragma unroll
;             for (int i = 0; i < 16; ++i) { const int l2 = i ^ j; if (l2 > i) CE_DESC(i, l2); }
	v_min_u32_e32 v3, v3, v4
	v_max_u32_e32 v4, v13, v10
	v_min_u32_e32 v10, v13, v10
	v_max_u32_e32 v13, v11, v9
	v_min_u32_e32 v9, v11, v9
	v_max_u32_e32 v11, v12, v8
	v_min_u32_e32 v8, v12, v8
	v_max_u32_e32 v12, v14, v15
	v_min_u32_e32 v14, v14, v15
	v_max_u32_e32 v15, v16, v20
	v_min_u32_e32 v16, v16, v20
	v_max_u32_e32 v20, v23, v22
	v_min_u32_e32 v22, v23, v22
	v_max_u32_e32 v23, v18, v21
	v_min_u32_e32 v18, v18, v21
	v_max_u32_e32 v21, v17, v19
	v_min_u32_e32 v17, v17, v19
	v_max_u32_e32 v19, v30, v2
	v_min_u32_e32 v2, v30, v2
	v_max_u32_e32 v30, v28, v26
	v_min_u32_e32 v26, v28, v26
	v_max_u32_e32 v28, v29, v25
	v_min_u32_e32 v25, v29, v25
	v_max_u32_e32 v29, v31, v27
	v_min_u32_e32 v27, v31, v27
	v_max_u32_e32 v31, v33, v32
	v_min_u32_e32 v32, v33, v32
	v_max_u32_e32 v33, v6, v24
	v_min_u32_e32 v6, v6, v24
	v_max_u32_e32 v24, v34, v7
	v_min_u32_e32 v7, v34, v7
	v_max_u32_e32 v34, v5, v3
	v_min_u32_e32 v3, v5, v3
	v_max_u32_e32 v5, v9, v10
	v_min_u32_e32 v9, v9, v10
	v_max_u32_e32 v10, v13, v4
	v_min_u32_e32 v4, v13, v4
	v_max_u32_e32 v13, v14, v8
	v_min_u32_e32 v8, v14, v8
	v_max_u32_e32 v14, v12, v11
	v_min_u32_e32 v11, v12, v11
	v_max_u32_e32 v12, v15, v20
	v_min_u32_e32 v15, v15, v20
	v_max_u32_e32 v20, v16, v22
	v_min_u32_e32 v16, v16, v22
	v_max_u32_e32 v22, v23, v21
	v_min_u32_e32 v21, v23, v21
	v_max_u32_e32 v23, v18, v17
	v_min_u32_e32 v17, v18, v17
	v_max_u32_e32 v18, v26, v2
	v_min_u32_e32 v2, v26, v2
	v_max_u32_e32 v26, v30, v19
	v_min_u32_e32 v19, v30, v19
	v_max_u32_e32 v30, v27, v25
	v_min_u32_e32 v25, v27, v25
	v_max_u32_e32 v27, v29, v28
	v_min_u32_e32 v28, v29, v28
	v_max_u32_e32 v29, v31, v9
	v_min_u32_e32 v9, v31, v9
	v_max_u32_e32 v31, v32, v5
	v_min_u32_e32 v5, v32, v5
	v_max_u32_e32 v32, v33, v4
	v_min_u32_e32 v4, v33, v4
	v_max_u32_e32 v33, v6, v10
	v_min_u32_e32 v6, v6, v10
	v_max_u32_e32 v10, v24, v8
	v_min_u32_e32 v8, v24, v8
	v_max_u32_e32 v24, v7, v13
	v_min_u32_e32 v7, v7, v13
	v_max_u32_e32 v13, v34, v11
	v_min_u32_e32 v11, v34, v11
	v_max_u32_e32 v34, v3, v14
	v_min_u32_e32 v3, v3, v14
	v_max_u32_e32 v14, v2, v12
	v_min_u32_e32 v2, v2, v12
	v_max_u32_e32 v12, v18, v15
	v_min_u32_e32 v15, v18, v15
	v_max_u32_e32 v18, v19, v20
	v_min_u32_e32 v19, v19, v20
	v_max_u32_e32 v20, v26, v16
	v_min_u32_e32 v16, v26, v16
	v_max_u32_e32 v26, v25, v22
	v_min_u32_e32 v22, v25, v22
	v_max_u32_e32 v25, v30, v21
	v_min_u32_e32 v21, v30, v21
	v_max_u32_e32 v30, v28, v23
	v_min_u32_e32 v23, v28, v23
	v_max_u32_e32 v28, v27, v17
	v_min_u32_e32 v17, v27, v17
	v_max_u32_e32 v27, v29, v10
	v_min_u32_e32 v10, v29, v10
	v_max_u32_e32 v29, v31, v24
	v_min_u32_e32 v24, v31, v24
	v_max_u32_e32 v31, v32, v13
	v_min_u32_e32 v13, v32, v13
	v_max_u32_e32 v32, v33, v34
	v_min_u32_e32 v33, v33, v34
	v_max_u32_e32 v34, v9, v8
	v_min_u32_e32 v8, v9, v8
	v_max_u32_e32 v9, v5, v7
	v_min_u32_e32 v5, v5, v7
	v_max_u32_e32 v7, v4, v11
	v_min_u32_e32 v4, v4, v11
	v_max_u32_e32 v11, v6, v3
	v_min_u32_e32 v3, v6, v3
	v_max_u32_e32 v6, v22, v2
	v_min_u32_e32 v2, v22, v2
	v_max_u32_e32 v22, v21, v15
	v_min_u32_e32 v15, v21, v15
	v_max_u32_e32 v21, v23, v19
	v_min_u32_e32 v19, v23, v19
	v_max_u32_e32 v23, v17, v16
	v_min_u32_e32 v16, v17, v16
	v_max_u32_e32 v17, v26, v14
	v_min_u32_e32 v14, v26, v14
	v_max_u32_e32 v26, v25, v12
	v_min_u32_e32 v12, v25, v12
	v_max_u32_e32 v25, v30, v18
	v_min_u32_e32 v18, v30, v18
	v_max_u32_e32 v30, v28, v20
	v_min_u32_e32 v20, v28, v20
	v_max_u32_e32 v28, v27, v31
	v_min_u32_e32 v27, v27, v31
	v_max_u32_e32 v31, v29, v32
	v_min_u32_e32 v29, v29, v32
	v_max_u32_e32 v32, v10, v13
	v_min_u32_e32 v10, v10, v13
	v_max_u32_e32 v13, v24, v33
	v_min_u32_e32 v24, v24, v33
	v_max_u32_e32 v33, v34, v7
	v_min_u32_e32 v7, v34, v7
	v_max_u32_e32 v34, v9, v11
	v_min_u32_e32 v9, v9, v11
	v_max_u32_e32 v11, v8, v4
	v_min_u32_e32 v4, v8, v4
	v_max_u32_e32 v8, v5, v3
	v_min_u32_e32 v3, v5, v3
	v_max_u32_e32 v5, v19, v2
	v_min_u32_e32 v2, v19, v2
	v_max_u32_e32 v19, v16, v15
	v_min_u32_e32 v15, v16, v15
	v_max_u32_e32 v16, v21, v6
	v_min_u32_e32 v6, v21, v6
	v_max_u32_e32 v21, v23, v22
	v_min_u32_e32 v22, v23, v22
	v_max_u32_e32 v23, v18, v14
	v_min_u32_e32 v14, v18, v14
	v_max_u32_e32 v18, v20, v12
	v_min_u32_e32 v12, v20, v12
	v_max_u32_e32 v20, v25, v17
	v_min_u32_e32 v17, v25, v17
	v_max_u32_e32 v25, v30, v26
	v_min_u32_e32 v26, v30, v26
	v_min_u32_e32 v30, v28, v31
	v_min_u32_e32 v35, v27, v29
	v_min_u32_e32 v36, v32, v13
	v_min_u32_e32 v37, v10, v24
	v_min_u32_e32 v38, v33, v34
	v_min_u32_e32 v39, v7, v9
	v_min_u32_e32 v40, v11, v8
	v_min_u32_e32 v41, v4, v3
	v_min_u32_e32 v42, v15, v2
	v_min_u32_e32 v43, v19, v5
	v_min_u32_e32 v44, v22, v6
	v_min_u32_e32 v45, v21, v16
	v_min_u32_e32 v46, v12, v14
	v_min_u32_e32 v47, v18, v23
	v_min_u32_e32 v51, v26, v17
	v_min_u32_e32 v52, v25, v20
	v_max3_u32 v20, v41, v25, v20
	v_max3_u32 v25, v28, v31, v42
	v_max3_u32 v2, v30, v15, v2
	v_max3_u32 v15, v27, v29, v43
	v_max3_u32 v5, v35, v19, v5
	v_max3_u32 v13, v32, v13, v44
	v_max3_u32 v6, v36, v22, v6
	v_max3_u32 v10, v10, v24, v45
	v_max3_u32 v16, v37, v21, v16
	v_max3_u32 v19, v33, v34, v46
	v_max3_u32 v12, v38, v12, v14
	v_max3_u32 v7, v7, v9, v47
	v_max3_u32 v9, v39, v18, v23
	v_max3_u32 v8, v11, v8, v51
	v_max3_u32 v11, v40, v26, v17
	v_max3_u32 v3, v4, v3, v52
	v_max_u32_e32 v4, v25, v19
	v_min_u32_e32 v14, v25, v19
	v_max_u32_e32 v17, v2, v12
	v_min_u32_e32 v2, v2, v12
	v_max_u32_e32 v12, v15, v7
	v_min_u32_e32 v7, v15, v7
	v_max_u32_e32 v15, v5, v9
	v_min_u32_e32 v5, v5, v9
	v_max_u32_e32 v9, v13, v8
	v_min_u32_e32 v8, v13, v8
	v_max_u32_e32 v13, v6, v11
	v_min_u32_e32 v6, v6, v11
	v_max_u32_e32 v11, v10, v3
	v_min_u32_e32 v3, v10, v3
; #define CE_DESC(a_, b_) do { const unsigned hi_ = max(x[a_], x[b_]), lo_ = min(x[a_], x[b_]); x[a_] = hi_; x[b_] = lo_; } while (0)
; __device__ __forceinline__ void peer_score_unit(const Frame& F, int l, int unit) {
;     ...
;         for (int j = 8; j > 0; j >>= 1)
; #pragma unroll
;             for (int i = 0; i < 16; ++i) { const int l2 = i ^ j; if (l2 > i) CE_DESC(i, l2); }
;     ...
;         MERGE_LEVEL(0xB1);
;         MERGE_LEVEL(0x4E);
	v_max_u32_e32 v10, v16, v20
	v_min_u32_e32 v16, v16, v20
	v_max_u32_e32 v18, v4, v9
	v_min_u32_e32 v4, v4, v9
	v_max_u32_e32 v9, v17, v13
	v_min_u32_e32 v13, v17, v13
	v_max_u32_e32 v17, v12, v11
	v_min_u32_e32 v11, v12, v11
	v_max_u32_e32 v12, v15, v10
	v_min_u32_e32 v10, v15, v10
	v_max_u32_e32 v15, v14, v8
	v_min_u32_e32 v8, v14, v8
	v_max_u32_e32 v14, v2, v6
	v_min_u32_e32 v2, v2, v6
	v_max_u32_e32 v6, v7, v3
	v_min_u32_e32 v3, v7, v3
	v_max_u32_e32 v7, v5, v16
	v_min_u32_e32 v5, v5, v16
	v_max_u32_e32 v16, v18, v17
	v_min_u32_e32 v17, v18, v17
	v_max_u32_e32 v18, v9, v12
	v_min_u32_e32 v9, v9, v12
	v_max_u32_e32 v12, v4, v11
	v_min_u32_e32 v4, v4, v11
	v_max_u32_e32 v11, v13, v10
	v_min_u32_e32 v10, v13, v10
	v_max_u32_e32 v13, v15, v6
	v_min_u32_e32 v6, v15, v6
	v_max_u32_e32 v15, v14, v7
	v_min_u32_e32 v7, v14, v7
	v_max_u32_e32 v14, v8, v3
	v_min_u32_e32 v3, v8, v3
	v_max_u32_e32 v8, v2, v5
	v_min_u32_e32 v2, v2, v5
	v_max_u32_e32 v5, v16, v18
	v_min_u32_e32 v16, v16, v18
	v_max_u32_e32 v18, v17, v9
	v_min_u32_e32 v9, v17, v9
	v_max_u32_e32 v17, v12, v11
	v_min_u32_e32 v11, v12, v11
	v_max_u32_e32 v12, v4, v10
	v_min_u32_e32 v4, v4, v10
	v_max_u32_e32 v10, v13, v15
	v_min_u32_e32 v13, v13, v15
	v_max_u32_e32 v15, v6, v7
	v_min_u32_e32 v6, v6, v7
	v_max_u32_e32 v7, v14, v8
	v_min_u32_e32 v8, v14, v8
	v_max_u32_e32 v14, v3, v2
	v_min_u32_e32 v2, v3, v2
	v_max_u32_dpp v19, v8, v18 quad_perm:[1,0,3,2] row_mask:0xf bank_mask:0xf bound_ctrl:1
	v_max_u32_dpp v20, v7, v9 quad_perm:[1,0,3,2] row_mask:0xf bank_mask:0xf bound_ctrl:1
	v_max_u32_dpp v3, v5, v2 quad_perm:[1,0,3,2] row_mask:0xf bank_mask:0xf bound_ctrl:1
	v_max_u32_dpp v2, v2, v5 quad_perm:[1,0,3,2] row_mask:0xf bank_mask:0xf bound_ctrl:1
	v_max_u32_dpp v5, v14, v16 quad_perm:[1,0,3,2] row_mask:0xf bank_mask:0xf bound_ctrl:1
	v_max_u32_dpp v21, v6, v17 quad_perm:[1,0,3,2] row_mask:0xf bank_mask:0xf bound_ctrl:1
	v_max_u32_dpp v22, v15, v11 quad_perm:[1,0,3,2] row_mask:0xf bank_mask:0xf bound_ctrl:1
	v_max_u32_dpp v23, v13, v12 quad_perm:[1,0,3,2] row_mask:0xf bank_mask:0xf bound_ctrl:1
	v_max_u32_dpp v24, v10, v4 quad_perm:[1,0,3,2] row_mask:0xf bank_mask:0xf bound_ctrl:1
	v_max_u32_dpp v4, v4, v10 quad_perm:[1,0,3,2] row_mask:0xf bank_mask:0xf bound_ctrl:1
	v_max_u32_dpp v10, v12, v13 quad_perm:[1,0,3,2] row_mask:0xf bank_mask:0xf bound_ctrl:1
	v_max_u32_dpp v11, v11, v15 quad_perm:[1,0,3,2] row_mask:0xf bank_mask:0xf bound_ctrl:1
	v_max_u32_dpp v6, v17, v6 quad_perm:[1,0,3,2] row_mask:0xf bank_mask:0xf bound_ctrl:1
	v_max_u32_dpp v7, v9, v7 quad_perm:[1,0,3,2] row_mask:0xf bank_mask:0xf bound_ctrl:1
	v_max_u32_dpp v8, v18, v8 quad_perm:[1,0,3,2] row_mask:0xf bank_mask:0xf bound_ctrl:1
	v_max_u32_dpp v9, v16, v14 quad_perm:[1,0,3,2] row_mask:0xf bank_mask:0xf bound_ctrl:1
	v_max_u32_e32 v12, v2, v4
	v_min_u32_e32 v2, v2, v4
	v_max_u32_e32 v4, v5, v10
	v_min_u32_e32 v5, v5, v10
	v_max_u32_e32 v10, v19, v11
	v_min_u32_e32 v11, v19, v11
	v_max_u32_e32 v13, v20, v6
	v_min_u32_e32 v6, v20, v6
	v_max_u32_e32 v14, v21, v7
	v_min_u32_e32 v7, v21, v7
	v_max_u32_e32 v15, v22, v8
	v_min_u32_e32 v8, v22, v8
	v_max_u32_e32 v16, v23, v9
	v_min_u32_e32 v9, v23, v9
	v_max_u32_e32 v17, v24, v3
	v_min_u32_e32 v3, v24, v3
	v_max_u32_e32 v18, v12, v14
	v_min_u32_e32 v12, v12, v14
	v_max_u32_e32 v14, v4, v15
	v_min_u32_e32 v4, v4, v15
	v_max_u32_e32 v15, v10, v16
	v_min_u32_e32 v10, v10, v16
	v_max_u32_e32 v16, v13, v17
	v_min_u32_e32 v13, v13, v17
	v_max_u32_e32 v17, v2, v7
	v_min_u32_e32 v2, v2, v7
	v_max_u32_e32 v7, v5, v8
	v_min_u32_e32 v5, v5, v8
	v_max_u32_e32 v8, v11, v9
	v_min_u32_e32 v9, v11, v9
	v_max_u32_e32 v11, v6, v3
	v_min_u32_e32 v3, v6, v3
	v_max_u32_e32 v6, v18, v15
	v_min_u32_e32 v15, v18, v15
	v_max_u32_e32 v18, v14, v16
	v_min_u32_e32 v14, v14, v16
	v_max_u32_e32 v16, v12, v10
	v_min_u32_e32 v10, v12, v10
	v_max_u32_e32 v12, v4, v13
	v_min_u32_e32 v19, v4, v13
	v_max_u32_e32 v20, v17, v8
	v_min_u32_e32 v8, v17, v8
	v_max_u32_e32 v17, v7, v11
	v_min_u32_e32 v7, v7, v11
	v_max_u32_e32 v21, v2, v9
	v_min_u32_e32 v23, v2, v9
	v_max_u32_e32 v24, v5, v3
	v_min_u32_e32 v25, v5, v3
	v_max_u32_e32 v13, v6, v18
	v_min_u32_e32 v4, v6, v18
	v_max_u32_e32 v11, v15, v14
	v_min_u32_e32 v2, v15, v14
	v_max_u32_e32 v14, v16, v12
	v_min_u32_e32 v5, v16, v12
	v_max_u32_e32 v12, v10, v19
	v_min_u32_e32 v3, v10, v19
	v_max_u32_e32 v19, v20, v17
	v_min_u32_e32 v9, v20, v17
	v_max_u32_e32 v17, v8, v7
	v_min_u32_e32 v6, v8, v7
	v_max_u32_e32 v22, v21, v24
	v_min_u32_e32 v10, v21, v24
	v_max_u32_e32 v18, v23, v25
	v_min_u32_e32 v7, v23, v25
	v_mov_b32_e32 v8, v201
	v_mov_b32_e32 v20, v201
	v_mov_b32_e32 v15, v201
	v_mov_b32_e32 v24, v201
	v_mov_b32_e32 v16, v201
	v_mov_b32_e32 v25, v201
	v_mov_b32_e32 v23, v201
	v_mov_b32_e32 v29, v201
	v_mov_b32_e32 v21, v201
	v_mov_b32_e32 v28, v201
	v_mov_b32_e32 v26, v201
	v_mov_b32_e32 v31, v201
	v_mov_b32_e32 v27, v201
	v_mov_b32_e32 v32, v201
	v_mov_b32_e32 v30, v201
	v_mov_b32_e32 v33, v201
	v_mov_b32_dpp v8, v13 quad_perm:[2,3,0,1] row_mask:0xf bank_mask:0xf
	v_mov_b32_dpp v20, v4 quad_perm:[2,3,0,1] row_mask:0xf bank_mask:0xf
	v_mov_b32_dpp v15, v11 quad_perm:[2,3,0,1] row_mask:0xf bank_mask:0xf
	v_mov_b32_dpp v24, v2 quad_perm:[2,3,0,1] row_mask:0xf bank_mask:0xf
	v_mov_b32_dpp v16, v14 quad_perm:[2,3,0,1] row_mask:0xf bank_mask:0xf
	v_mov_b32_dpp v25, v5 quad_perm:[2,3,0,1] row_mask:0xf bank_mask:0xf
	v_mov_b32_dpp v23, v12 quad_perm:[2,3,0,1] row_mask:0xf bank_mask:0xf
	v_mov_b32_dpp v29, v3 quad_perm:[2,3,0,1] row_mask:0xf bank_mask:0xf
	v_mov_b32_dpp v21, v19 quad_perm:[2,3,0,1] row_mask:0xf bank_mask:0xf
	v_mov_b32_dpp v28, v9 quad_perm:[2,3,0,1] row_mask:0xf bank_mask:0xf
	v_mov_b32_dpp v26, v17 quad_perm:[2,3,0,1] row_mask:0xf bank_mask:0xf
	v_mov_b32_dpp v31, v6 quad_perm:[2,3,0,1] row_mask:0xf bank_mask:0xf
	v_mov_b32_dpp v27, v22 quad_perm:[2,3,0,1] row_mask:0xf bank_mask:0xf
	v_mov_b32_dpp v32, v10 quad_perm:[2,3,0,1] row_mask:0xf bank_mask:0xf
	v_mov_b32_dpp v30, v18 quad_perm:[2,3,0,1] row_mask:0xf bank_mask:0xf
	v_mov_b32_dpp v33, v7 quad_perm:[2,3,0,1] row_mask:0xf bank_mask:0xf
	s_and_saveexec_b64 s[0:1], vcc
	s_cbranch_execz .LBB0_2049
; __device__ __forceinline__ void peer_score_unit(const Frame& F, int l, int unit) {
;     ...
;         MERGE_LEVEL(0xB1);
;         MERGE_LEVEL(0x4E);
;     ...
;         if (qd == 0) {
; #pragma unroll
;             for (int k = 0; k < 16; ++k) { const int n = 127 - (int)(x[k] & 127u); SI[row * 16 + k] = n; SV[row * 16 + k] = S[row * 129 + n]; }
;         }
	v_max_u32_e32 v13, v13, v33
	v_max_u32_e32 v19, v19, v29
	v_max_u32_e32 v14, v14, v31
	v_max_u32_e32 v22, v22, v24
	v_max_u32_e32 v11, v11, v32
	v_max_u32_e32 v17, v17, v25
	v_max_u32_e32 v12, v12, v28
	v_max_u32_e32 v18, v18, v20
	v_max_u32_e32 v30, v4, v30
	v_max_u32_e32 v9, v9, v23
	v_max_u32_e32 v26, v5, v26
	v_max_u32_e32 v10, v10, v15
	v_max_u32_e32 v27, v2, v27
	v_max_u32_e32 v6, v6, v16
	v_max_u32_e32 v21, v3, v21
	v_max_u32_e32 v7, v7, v8
	v_min_u32_e32 v29, v13, v19
	v_min_u32_e32 v24, v14, v22
	v_min_u32_e32 v25, v11, v17
	v_min_u32_e32 v20, v12, v18
	v_min_u32_e32 v23, v30, v9
	v_min_u32_e32 v15, v26, v10
	v_min_u32_e32 v16, v27, v6
	v_min_u32_e32 v8, v21, v7
	v_min_u32_e32 v31, v29, v24
	v_min_u32_e32 v28, v25, v20
	v_min_u32_e32 v4, v23, v15
	v_min_u32_e32 v5, v16, v8
	v_max_u32_e32 v24, v29, v24
	v_max_u32_e32 v20, v25, v20
	v_max_u32_e32 v15, v23, v15
	v_max_u32_e32 v8, v16, v8
	v_min_u32_e32 v25, v24, v20
	v_min_u32_e32 v16, v15, v8
	v_max_u32_e32 v20, v24, v20
	v_max_u32_e32 v8, v15, v8
	v_max_u32_e32 v13, v13, v19
	v_max_u32_e32 v14, v14, v22
	v_max_u32_e32 v11, v11, v17
	v_max_u32_e32 v12, v12, v18
	v_max_u32_e32 v9, v30, v9
	v_max_u32_e32 v10, v26, v10
	v_max_u32_e32 v6, v27, v6
	v_max_u32_e32 v7, v21, v7
	v_min_u32_e32 v15, v20, v8
	v_max_u32_e32 v8, v20, v8
	v_min_u32_e32 v19, v13, v14
	v_min_u32_e32 v17, v11, v12
	v_min_u32_e32 v20, v9, v10
	v_min_u32_e32 v21, v6, v7
	v_max_u32_e32 v13, v13, v14
	v_max_u32_e32 v11, v11, v12
	v_max_u32_e32 v9, v9, v10
	v_max_u32_e32 v6, v6, v7
	v_min_u32_e32 v12, v13, v11
	v_min_u32_e32 v7, v9, v6
	v_min_u32_e32 v10, v12, v7
	v_max_u32_e32 v12, v12, v7
	v_max_u32_e32 v7, v13, v11
	v_max_u32_e32 v6, v9, v6
	v_min_u32_e32 v9, v7, v6
	v_max_u32_e32 v6, v7, v6
	v_xor_b32_e32 v6, -1, v6
	v_and_b32_e32 v6, 0x7f, v6
	v_xor_b32_e32 v7, -1, v9
	v_lshl_add_u32 v9, v6, 2, v0
	ds_read_b32 v9, v9
	v_lshlrev_b32_e32 v11, 6, v1
	v_add_u32_e32 v1, s58, v11
	v_and_b32_e32 v7, 0x7f, v7
	v_add_u32_e32 v13, s57, v11
	s_waitcnt lgkmcnt(0)
	ds_write_b32 v1, v9
	ds_write_b64 v13, v[6:7]
	v_lshl_add_u32 v6, v7, 2, v0
	ds_read_b32 v6, v6
	v_min_u32_e32 v18, v19, v17
	v_max_u32_e32 v17, v19, v17
	v_max_u32_e32 v19, v20, v21
	v_min_u32_e32 v22, v20, v21
	s_waitcnt lgkmcnt(0)
	ds_write_b32 v1, v6 offset:4
	v_or_b32_e32 v6, 8, v11
	v_add_u32_e32 v9, s57, v6
	v_add_u32_e32 v13, s58, v6
	v_xor_b32_e32 v6, -1, v10
	v_xor_b32_e32 v10, -1, v12
	v_and_b32_e32 v7, 0x7f, v6
	v_and_b32_e32 v6, 0x7f, v10
	v_lshl_add_u32 v10, v6, 2, v0
	ds_read_b32 v10, v10
	s_waitcnt lgkmcnt(0)
	ds_write_b32 v13, v10
	ds_write_b64 v9, v[6:7]
	v_lshl_add_u32 v6, v7, 2, v0
	ds_read_b32 v6, v6
	v_min_u32_e32 v20, v17, v19
	v_max_u32_e32 v17, v17, v19
	v_xor_b32_e32 v12, -1, v17
	v_min_u32_e32 v24, v18, v22
	s_waitcnt lgkmcnt(0)
	ds_write_b32 v1, v6 offset:12
	v_or_b32_e32 v6, 16, v11
	v_add_u32_e32 v9, s57, v6
	v_add_u32_e32 v10, s58, v6
	v_xor_b32_e32 v6, -1, v20
	v_and_b32_e32 v7, 0x7f, v6
	v_and_b32_e32 v6, 0x7f, v12
	v_lshl_add_u32 v12, v6, 2, v0
	ds_read_b32 v12, v12
	s_waitcnt lgkmcnt(0)
	ds_write_b32 v10, v12
	ds_write_b64 v9, v[6:7]
	v_lshl_add_u32 v6, v7, 2, v0
	ds_read_b32 v6, v6
	v_max_u32_e32 v18, v18, v22
	v_xor_b32_e32 v12, -1, v18
	v_xor_b32_e32 v8, -1, v8
	v_min_u32_e32 v23, v25, v16
	s_waitcnt lgkmcnt(0)
	ds_write_b32 v1, v6 offset:20
	v_or_b32_e32 v6, 24, v11
	v_add_u32_e32 v9, s57, v6
	v_add_u32_e32 v10, s58, v6
	v_xor_b32_e32 v6, -1, v24
	v_and_b32_e32 v7, 0x7f, v6
	v_and_b32_e32 v6, 0x7f, v12
	v_lshl_add_u32 v12, v6, 2, v0
	ds_read_b32 v12, v12
	s_waitcnt lgkmcnt(0)
	ds_write_b32 v10, v12
	ds_write_b64 v9, v[6:7]
	v_lshl_add_u32 v6, v7, 2, v0
	ds_read_b32 v6, v6
	v_max_u32_e32 v16, v25, v16
	v_min_u32_e32 v32, v31, v28
	v_min_u32_e32 v2, v4, v5
	v_max_u32_e32 v28, v31, v28
	s_waitcnt lgkmcnt(0)
	ds_write_b32 v1, v6 offset:28
	v_or_b32_e32 v6, 32, v11
	v_add_u32_e32 v9, s57, v6
	v_add_u32_e32 v10, s58, v6
	v_xor_b32_e32 v6, -1, v15
	v_and_b32_e32 v7, 0x7f, v6
	v_and_b32_e32 v6, 0x7f, v8
	v_lshl_add_u32 v8, v6, 2, v0
	ds_read_b32 v8, v8
	s_waitcnt lgkmcnt(0)
	ds_write_b32 v10, v8
	ds_write_b64 v9, v[6:7]
	v_lshl_add_u32 v6, v7, 2, v0
	ds_read_b32 v6, v6
	v_xor_b32_e32 v10, -1, v16
	v_max_u32_e32 v4, v4, v5
	v_min_u32_e32 v5, v28, v4
	v_max_u32_e32 v4, v28, v4
	s_waitcnt lgkmcnt(0)
	ds_write_b32 v1, v6 offset:36
	v_or_b32_e32 v6, 40, v11
	v_add_u32_e32 v8, s57, v6
	v_add_u32_e32 v9, s58, v6
	v_xor_b32_e32 v6, -1, v23
	v_and_b32_e32 v7, 0x7f, v6
	v_and_b32_e32 v6, 0x7f, v10
	v_lshl_add_u32 v10, v6, 2, v0
	ds_read_b32 v10, v10
	s_waitcnt lgkmcnt(0)
	ds_write_b32 v9, v10
	ds_write_b64 v8, v[6:7]
	v_lshl_add_u32 v6, v7, 2, v0
	ds_read_b32 v6, v6
	v_xor_b32_e32 v4, -1, v4
	v_and_b32_e32 v4, 0x7f, v4
	v_lshl_add_u32 v8, v4, 2, v0
	v_xor_b32_e32 v5, -1, v5
	s_waitcnt lgkmcnt(0)
	ds_write_b32 v1, v6 offset:44
	ds_read_b32 v8, v8
	v_or_b32_e32 v6, 48, v11
	v_add_u32_e32 v7, s57, v6
	v_add_u32_e32 v6, s58, v6
	v_and_b32_e32 v5, 0x7f, v5
	s_waitcnt lgkmcnt(0)
	ds_write_b32 v6, v8
	ds_write_b64 v7, v[4:5]
	v_lshl_add_u32 v4, v5, 2, v0
	ds_read_b32 v4, v4
	v_min_u32_e32 v3, v32, v2
	v_max_u32_e32 v2, v32, v2
	v_xor_b32_e32 v2, -1, v2
	v_and_b32_e32 v2, 0x7f, v2
	s_waitcnt lgkmcnt(0)
	ds_write_b32 v1, v4 offset:52
	v_lshl_add_u32 v6, v2, 2, v0
	ds_read_b32 v6, v6
	v_or_b32_e32 v4, 56, v11
	v_xor_b32_e32 v3, -1, v3
	v_add_u32_e32 v5, s57, v4
	v_add_u32_e32 v4, s58, v4
	v_and_b32_e32 v3, 0x7f, v3
	s_waitcnt lgkmcnt(0)
	ds_write_b32 v4, v6
	ds_write_b64 v5, v[2:3]
	v_lshl_add_u32 v0, v3, 2, v0
	ds_read_b32 v0, v0
	s_waitcnt lgkmcnt(0)
	ds_write_b32 v1, v0 offset:60
; #define LAS __attribute__((address_space(3)))
; __device__ __forceinline__ void peer_score_unit(const Frame& F, int l, int unit) {
;     ...
;         const int cc = wave >> 2, nb = wave & 3, rl = lane & 31, h = lane >> 5;
;         const bf16_t* SK = (const bf16_t*)(ws + WS_SK) + ((size_t)((l * 8 + hd) * 2 + cc) * 128 + 32 * nb + rl) * 128 + 8 * h;
;         bf16x8 bfr[8];
; #pragma unroll
;         for (int ks = 0; ks < 8; ++ks) bfr[ks] = *(const bf16x8*)(SK + 16 * ks);
;         bf16x8 afr[2][8];
; #pragma unroll
;         for (int tb = 0; tb < 2; ++tb) { const bf16_t* QP = (const bf16_t*)(ws + WS_QP) + (size_t)(r0 + 32 * tb + rl) * D + hd * 256 + cc * 128 + 8 * h;
; #pragma unroll
;             for (int ks = 0; ks < 8; ++ks) afr[tb][ks] = *(const bf16x8*)(QP + 16 * ks); }
;     ...
;     for (int repc = 0; repc < P9_REP_C; ++repc) if (tid < 64) {
;         float a[16], c[16]; int p[16];
;         const LAS float* bl = SV + (64 + tid) * 16;
;         const float b0v = bl[0];
; #pragma unroll
;         for (int i = 0; i < 16; ++i) { a[i] = SV[tid * 16 + i]; c[i] = a[i] + b0v; p[i] = 0; }
;         float fv[16]; int fi[16];
; #pragma unroll
;         for (int k = 0; k < 16; ++k) {
;             float best = c[0]; int bi = 0;
; #pragma unroll
;             for (int i = 1; i < 16; ++i) if (c[i] > best) { best = c[i]; bi = i; }
;             int pj = 0, lim = 16;
; #pragma unroll
;             for (int i = 0; i < 16; ++i) { pj = (i == bi) ? p[i] : pj; lim = (i == bi) ? 16 / (i + 1) : lim; }
;             fv[k] = best; fi[k] = bi * 16 + pj;
;             const int np = pj + 1; const float nb = bl[np & 15];
; #pragma unroll
;             for (int i = 0; i < 16; ++i) if (i == bi) { p[i] = np; c[i] = (np < lim) ? a[i] + nb : -INFINITY; }
.LBB0_2049:
	s_or_b64 exec, exec, s[0:1]
	v_cmp_gt_i32_e32 vcc, 64, v50
	s_waitcnt lgkmcnt(0)
	s_barrier
	s_mov_b32 s12, 0x1112347f
	s_mov_b32 s13, 0
	s_mov_b32 s20, 0x10001
	v_and_b32_e32 v138, 15, v50
	v_lshlrev_b32_e32 v139, 2, v138
	v_lshl_add_u32 v134, v50, 2, s58
	v_lshrrev_b64 v[140:141], v139, s[12:13]
	v_and_b32_e32 v135, -64, v134
	ds_read_b32 v114, v134
	ds_read_b32 v124, v134 offset:2048
	ds_read_b32 v115, v135 offset:4096
	ds_read_b32 v125, v135 offset:6144
	v_lshlrev_b32_e32 v113, 8, v138
	v_and_b32_e32 v140, 15, v140
	v_lshlrev_b32_e32 v142, 3, v50
	v_lshl_add_u32 v119, v140, 2, v113
	v_mov_b32_e32 v112, 0xff800000
	v_sub_u32_e32 v122, v135, v113
	v_add_u32_e32 v119, 4, v119
	v_and_b32_e32 v123, 0xffffff80, v142
	v_mov_b32_e32 v117, v113
	v_mov_b32_e32 v127, v113
	s_lshl_b32 s0, s7, 9
	s_lshl_b32 s1, s6, 6
	s_add_u32 s0, s0, s1
	s_add_u32 s16, s4, s0
	s_addc_u32 s17, s5, 0
	s_add_u32 s16, s16, 0x4a0d0000
	s_addc_u32 s17, s17, 0
	s_add_u32 s18, s16, 0x500000
	s_addc_u32 s19, s17, 0
	v_mov_b32_e32 v121, s87
	ds_read_b32 v120, v121 offset:8
	s_waitcnt lgkmcnt(0)
	s_nop 0
	v_readfirstlane_b32 s99, v120
	s_cmpk_lt_i32 s99, 0x500
	s_cbranch_scc0 .Lp9_nopf
	s_mov_b32 s7, s99
	s_and_b32 s6, s7, 7
	s_lshl_b32 s0, s6, 1
	s_add_i32 s0, s54, s0
	s_ashr_i32 s1, s0, 31
	v_mov_b32_e32 v0, v48
	v_mov_b32_e32 v50, v49
	s_lshl_b64 s[0:1], s[0:1], 7
	s_or_b64 s[0:1], s[0:1], s[46:47]
	v_and_b32_e32 v6, 31, v0
	v_ashrrev_i32_e32 v7, 5, v0
	v_or_b32_e32 v0, s0, v6
	v_mov_b32_e32 v1, s1
	v_lshlrev_b32_e32 v2, 3, v7
	s_mov_b64 s[4:5], s[42:43]
	v_lshlrev_b64 v[0:1], 8, v[0:1]
	v_ashrrev_i32_e32 v3, 31, v2
	v_lshlrev_b64 v[2:3], 1, v[2:3]
	v_lshl_add_u64 v[0:1], s[4:5], 0, v[0:1]
	v_lshl_add_u64 v[0:1], v[0:1], 0, v[2:3]
	s_mov_b64 s[0:1], 0xbc80000
	s_lshl_b32 s7, s7, 3
	v_lshl_add_u64 v[4:5], v[0:1], 0, s[0:1]
	s_lshl_b32 s0, s6, 9
	s_add_u32 s0, s4, s0
	s_addc_u32 s1, s5, 0
	s_mov_b32 s8, 0xbc80000
	s_add_u32 s0, s0, s50
	v_add_co_u32_e32 v0, vcc, s8, v0
	s_addc_u32 s1, s1, s51
	s_nop 0
	v_addc_co_u32_e32 v1, vcc, 0, v1, vcc
	s_andn2_b32 s7, s7, 63
	global_load_dwordx4 v[44:47], v[0:1], off
	global_load_dwordx4 v[40:43], v[4:5], off offset:32
	global_load_dwordx4 v[36:39], v[4:5], off offset:64
	global_load_dwordx4 v[32:35], v[4:5], off offset:96
	global_load_dwordx4 v[28:31], v[4:5], off offset:128
	global_load_dwordx4 v[16:19], v[4:5], off offset:160
	global_load_dwordx4 v[20:23], v[4:5], off offset:192
	global_load_dwordx4 v[24:27], v[4:5], off offset:224
	v_or_b32_e32 v0, s7, v6
	v_ashrrev_i32_e32 v1, 31, v0
	v_lshlrev_b64 v[4:5], 12, v[0:1]
	v_or_b32_e32 v0, 32, v0
	v_lshl_add_u64 v[2:3], s[0:1], 0, v[2:3]
	s_mov_b64 s[0:1], 0x44bd0000
	v_ashrrev_i32_e32 v1, 31, v0
	v_lshl_add_u64 v[2:3], v[2:3], 0, s[0:1]
	v_lshlrev_b64 v[0:1], 12, v[0:1]
	v_lshl_add_u64 v[0:1], v[2:3], 0, v[0:1]
	v_lshl_add_u64 v[4:5], v[2:3], 0, v[4:5]
	global_load_dwordx4 v[52:55], v[0:1], off offset:224
	global_load_dwordx4 v[56:59], v[0:1], off offset:192
	global_load_dwordx4 v[60:63], v[0:1], off offset:160
	global_load_dwordx4 v[64:67], v[0:1], off offset:128
	global_load_dwordx4 v[68:71], v[0:1], off offset:96
	global_load_dwordx4 v[72:75], v[0:1], off offset:64
	global_load_dwordx4 v[76:79], v[0:1], off offset:32
	global_load_dwordx4 v[80:83], v[0:1], off
	global_load_dwordx4 v[84:87], v[4:5], off offset:224
	global_load_dwordx4 v[88:91], v[4:5], off offset:192
	global_load_dwordx4 v[92:95], v[4:5], off offset:160
	global_load_dwordx4 v[96:99], v[4:5], off offset:128
	global_load_dwordx4 v[100:103], v[4:5], off offset:96
	global_load_dwordx4 v[104:107], v[4:5], off offset:64
	global_load_dwordx4 v[108:111], v[4:5], off offset:32
	global_load_dwordx4 v[0:3], v[4:5], off
.Lp9_nopf:
	s_waitcnt lgkmcnt(0)
	v_add_f32_e32 v118, v114, v115
	v_add_f32_e32 v128, v124, v125
	v_cmp_lt_u32_e32 vcc, v117, v119
	v_cmp_lt_u32_e64 s[10:11], v127, v119
	s_nop 0
	v_cndmask_b32_e32 v116, v112, v118, vcc
	v_cndmask_b32_e64 v126, v112, v128, s[10:11]
	s_nop 0
	v_max_f32_dpp v136, v116, v116 row_ror:8 row_mask:0xf bank_mask:0xf
	v_max_f32_dpp v137, v126, v126 row_ror:8 row_mask:0xf bank_mask:0xf
	s_nop 0
	v_max_f32_dpp v136, v136, v136 row_ror:4 row_mask:0xf bank_mask:0xf
	v_max_f32_dpp v137, v137, v137 row_ror:4 row_mask:0xf bank_mask:0xf
	s_nop 0
	v_max_f32_dpp v136, v136, v136 row_ror:2 row_mask:0xf bank_mask:0xf
	v_max_f32_dpp v137, v137, v137 row_ror:2 row_mask:0xf bank_mask:0xf
	s_nop 0
	v_max_f32_dpp v136, v136, v136 row_ror:1 row_mask:0xf bank_mask:0xf
	v_max_f32_dpp v137, v137, v137 row_ror:1 row_mask:0xf bank_mask:0xf
	v_cmp_eq_f32_e32 vcc, v116, v136
	v_cmp_eq_f32_e64 s[10:11], v126, v137
	s_sub_u32 s0, vcc_lo, s20
	s_subb_u32 s1, vcc_hi, s20
	s_andn2_b64 exec, vcc, s[0:1]
	ds_write_b64 v123, v[116:117] offset:0
	v_add_u32_e32 v117, 4, v117
	v_add_u32_e32 v121, v122, v117
	ds_read_b32 v115, v121 offset:4096
	s_sub_u32 s0, s10, s20
	s_subb_u32 s1, s11, s20
	s_andn2_b64 exec, s[10:11], s[0:1]
	ds_write_b64 v123, v[126:127] offset:4096
	v_add_u32_e32 v127, 4, v127
	v_add_u32_e32 v131, v122, v127
	ds_read_b32 v125, v131 offset:6144
	s_mov_b64 exec, -1
	s_waitcnt lgkmcnt(0)
; __device__ __forceinline__ void peer_score_unit(const Frame& F, int l, int unit) {
;     ...
; #pragma unroll
;         for (int k = 0; k < 16; ++k) {
;             float best = c[0]; int bi = 0;
; #pragma unroll
;             for (int i = 1; i < 16; ++i) if (c[i] > best) { best = c[i]; bi = i; }
;             int pj = 0, lim = 16;
; #pragma unroll
;             for (int i = 0; i < 16; ++i) { pj = (i == bi) ? p[i] : pj; lim = (i == bi) ? 16 / (i + 1) : lim; }
;             fv[k] = best; fi[k] = bi * 16 + pj;
;             const int np = pj + 1; const float nb = bl[np & 15];
; #pragma unroll
;             for (int i = 0; i < 16; ++i) if (i == bi) { p[i] = np; c[i] = (np < lim) ? a[i] + nb : -INFINITY; }
	v_add_f32_e32 v118, v114, v115
	v_add_f32_e32 v128, v124, v125
	v_cmp_lt_u32_e32 vcc, v117, v119
	v_cmp_lt_u32_e64 s[10:11], v127, v119
	s_nop 0
	v_cndmask_b32_e32 v116, v112, v118, vcc
	v_cndmask_b32_e64 v126, v112, v128, s[10:11]
	s_nop 0
	v_max_f32_dpp v120, v116, v116 row_ror:8 row_mask:0xf bank_mask:0xf
	v_max_f32_dpp v130, v126, v126 row_ror:8 row_mask:0xf bank_mask:0xf
	s_nop 0
	v_max_f32_dpp v120, v120, v120 row_ror:4 row_mask:0xf bank_mask:0xf
	v_max_f32_dpp v130, v130, v130 row_ror:4 row_mask:0xf bank_mask:0xf
	s_nop 0
	v_max_f32_dpp v120, v120, v120 row_ror:2 row_mask:0xf bank_mask:0xf
	v_max_f32_dpp v130, v130, v130 row_ror:2 row_mask:0xf bank_mask:0xf
	s_nop 0
	v_max_f32_dpp v120, v120, v120 row_ror:1 row_mask:0xf bank_mask:0xf
	v_max_f32_dpp v130, v130, v130 row_ror:1 row_mask:0xf bank_mask:0xf
	v_cmp_eq_f32_e32 vcc, v116, v120
	v_cmp_eq_f32_e64 s[10:11], v126, v130
	s_sub_u32 s0, vcc_lo, s20
	s_subb_u32 s1, vcc_hi, s20
	s_andn2_b64 exec, vcc, s[0:1]
	ds_write_b64 v123, v[116:117] offset:8
	v_add_u32_e32 v117, 4, v117
	v_add_u32_e32 v121, v122, v117
	ds_read_b32 v115, v121 offset:4096
	s_sub_u32 s0, s10, s20
	s_subb_u32 s1, s11, s20
	s_andn2_b64 exec, s[10:11], s[0:1]
	ds_write_b64 v123, v[126:127] offset:4104
	v_add_u32_e32 v127, 4, v127
	v_add_u32_e32 v131, v122, v127
	ds_read_b32 v125, v131 offset:6144
	s_mov_b64 exec, -1
	s_waitcnt lgkmcnt(0)
	v_add_f32_e32 v118, v114, v115
	v_add_f32_e32 v128, v124, v125
	v_cmp_lt_u32_e32 vcc, v117, v119
	v_cmp_lt_u32_e64 s[10:11], v127, v119
	s_nop 0
	v_cndmask_b32_e32 v116, v112, v118, vcc
	v_cndmask_b32_e64 v126, v112, v128, s[10:11]
	s_nop 0
	v_max_f32_dpp v120, v116, v116 row_ror:8 row_mask:0xf bank_mask:0xf
	v_max_f32_dpp v130, v126, v126 row_ror:8 row_mask:0xf bank_mask:0xf
	s_nop 0
	v_max_f32_dpp v120, v120, v120 row_ror:4 row_mask:0xf bank_mask:0xf
	v_max_f32_dpp v130, v130, v130 row_ror:4 row_mask:0xf bank_mask:0xf
	s_nop 0
	v_max_f32_dpp v120, v120, v120 row_ror:2 row_mask:0xf bank_mask:0xf
	v_max_f32_dpp v130, v130, v130 row_ror:2 row_mask:0xf bank_mask:0xf
	s_nop 0
	v_max_f32_dpp v120, v120, v120 row_ror:1 row_mask:0xf bank_mask:0xf
	v_max_f32_dpp v130, v130, v130 row_ror:1 row_mask:0xf bank_mask:0xf
	v_cmp_eq_f32_e32 vcc, v116, v120
	v_cmp_eq_f32_e64 s[10:11], v126, v130
	s_sub_u32 s0, vcc_lo, s20
	s_subb_u32 s1, vcc_hi, s20
	s_andn2_b64 exec, vcc, s[0:1]
	ds_write_b64 v123, v[116:117] offset:16
	v_add_u32_e32 v117, 4, v117
	v_add_u32_e32 v121, v122, v117
	ds_read_b32 v115, v121 offset:4096
	s_sub_u32 s0, s10, s20
	s_subb_u32 s1, s11, s20
	s_andn2_b64 exec, s[10:11], s[0:1]
	ds_write_b64 v123, v[126:127] offset:4112
	v_add_u32_e32 v127, 4, v127
	v_add_u32_e32 v131, v122, v127
	ds_read_b32 v125, v131 offset:6144
	s_mov_b64 exec, -1
	s_waitcnt lgkmcnt(0)
	v_add_f32_e32 v118, v114, v115
	v_add_f32_e32 v128, v124, v125
	v_cmp_lt_u32_e32 vcc, v117, v119
	v_cmp_lt_u32_e64 s[10:11], v127, v119
	s_nop 0
	v_cndmask_b32_e32 v116, v112, v118, vcc
	v_cndmask_b32_e64 v126, v112, v128, s[10:11]
	s_nop 0
	v_max_f32_dpp v120, v116, v116 row_ror:8 row_mask:0xf bank_mask:0xf
	v_max_f32_dpp v130, v126, v126 row_ror:8 row_mask:0xf bank_mask:0xf
	s_nop 0
	v_max_f32_dpp v120, v120, v120 row_ror:4 row_mask:0xf bank_mask:0xf
	v_max_f32_dpp v130, v130, v130 row_ror:4 row_mask:0xf bank_mask:0xf
	s_nop 0
	v_max_f32_dpp v120, v120, v120 row_ror:2 row_mask:0xf bank_mask:0xf
	v_max_f32_dpp v130, v130, v130 row_ror:2 row_mask:0xf bank_mask:0xf
	s_nop 0
	v_max_f32_dpp v120, v120, v120 row_ror:1 row_mask:0xf bank_mask:0xf
	v_max_f32_dpp v130, v130, v130 row_ror:1 row_mask:0xf bank_mask:0xf
	v_cmp_eq_f32_e32 vcc, v116, v120
	v_cmp_eq_f32_e64 s[10:11], v126, v130
	s_sub_u32 s0, vcc_lo, s20
	s_subb_u32 s1, vcc_hi, s20
	s_andn2_b64 exec, vcc, s[0:1]
	ds_write_b64 v123, v[116:117] offset:24
	v_add_u32_e32 v117, 4, v117
	v_add_u32_e32 v121, v122, v117
	ds_read_b32 v115, v121 offset:4096
	s_sub_u32 s0, s10, s20
	s_subb_u32 s1, s11, s20
	s_andn2_b64 exec, s[10:11], s[0:1]
	ds_write_b64 v123, v[126:127] offset:4120
	v_add_u32_e32 v127, 4, v127
	v_add_u32_e32 v131, v122, v127
	ds_read_b32 v125, v131 offset:6144
	s_mov_b64 exec, -1
	s_waitcnt lgkmcnt(0)
	v_add_f32_e32 v118, v114, v115
	v_add_f32_e32 v128, v124, v125
	v_cmp_lt_u32_e32 vcc, v117, v119
	v_cmp_lt_u32_e64 s[10:11], v127, v119
	s_nop 0
	v_cndmask_b32_e32 v116, v112, v118, vcc
	v_cndmask_b32_e64 v126, v112, v128, s[10:11]
	s_nop 0
	v_max_f32_dpp v120, v116, v116 row_ror:8 row_mask:0xf bank_mask:0xf
	v_max_f32_dpp v130, v126, v126 row_ror:8 row_mask:0xf bank_mask:0xf
	s_nop 0
	v_max_f32_dpp v120, v120, v120 row_ror:4 row_mask:0xf bank_mask:0xf
	v_max_f32_dpp v130, v130, v130 row_ror:4 row_mask:0xf bank_mask:0xf
	s_nop 0
	v_max_f32_dpp v120, v120, v120 row_ror:2 row_mask:0xf bank_mask:0xf
	v_max_f32_dpp v130, v130, v130 row_ror:2 row_mask:0xf bank_mask:0xf
	s_nop 0
	v_max_f32_dpp v120, v120, v120 row_ror:1 row_mask:0xf bank_mask:0xf
	v_max_f32_dpp v130, v130, v130 row_ror:1 row_mask:0xf bank_mask:0xf
	v_cmp_eq_f32_e32 vcc, v116, v120
	v_cmp_eq_f32_e64 s[10:11], v126, v130
	s_sub_u32 s0, vcc_lo, s20
	s_subb_u32 s1, vcc_hi, s20
	s_andn2_b64 exec, vcc, s[0:1]
	ds_write_b64 v123, v[116:117] offset:32
	v_add_u32_e32 v117, 4, v117
	v_add_u32_e32 v121, v122, v117
	ds_read_b32 v115, v121 offset:4096
	s_sub_u32 s0, s10, s20
	s_subb_u32 s1, s11, s20
	s_andn2_b64 exec, s[10:11], s[0:1]
	ds_write_b64 v123, v[126:127] offset:4128
	v_add_u32_e32 v127, 4, v127
	v_add_u32_e32 v131, v122, v127
	ds_read_b32 v125, v131 offset:6144
	s_mov_b64 exec, -1
	s_waitcnt lgkmcnt(0)
; __device__ __forceinline__ void peer_score_unit(const Frame& F, int l, int unit) {
;     ...
; #pragma unroll
;         for (int k = 0; k < 16; ++k) {
;             float best = c[0]; int bi = 0;
; #pragma unroll
;             for (int i = 1; i < 16; ++i) if (c[i] > best) { best = c[i]; bi = i; }
;             int pj = 0, lim = 16;
; #pragma unroll
;             for (int i = 0; i < 16; ++i) { pj = (i == bi) ? p[i] : pj; lim = (i == bi) ? 16 / (i + 1) : lim; }
;             fv[k] = best; fi[k] = bi * 16 + pj;
;             const int np = pj + 1; const float nb = bl[np & 15];
; #pragma unroll
;             for (int i = 0; i < 16; ++i) if (i == bi) { p[i] = np; c[i] = (np < lim) ? a[i] + nb : -INFINITY; }
	v_add_f32_e32 v118, v114, v115
	v_add_f32_e32 v128, v124, v125
	v_cmp_lt_u32_e32 vcc, v117, v119
	v_cmp_lt_u32_e64 s[10:11], v127, v119
	s_nop 0
	v_cndmask_b32_e32 v116, v112, v118, vcc
	v_cndmask_b32_e64 v126, v112, v128, s[10:11]
	s_nop 0
	v_max_f32_dpp v120, v116, v116 row_ror:8 row_mask:0xf bank_mask:0xf
	v_max_f32_dpp v130, v126, v126 row_ror:8 row_mask:0xf bank_mask:0xf
	s_nop 0
	v_max_f32_dpp v120, v120, v120 row_ror:4 row_mask:0xf bank_mask:0xf
	v_max_f32_dpp v130, v130, v130 row_ror:4 row_mask:0xf bank_mask:0xf
	s_nop 0
	v_max_f32_dpp v120, v120, v120 row_ror:2 row_mask:0xf bank_mask:0xf
	v_max_f32_dpp v130, v130, v130 row_ror:2 row_mask:0xf bank_mask:0xf
	s_nop 0
	v_max_f32_dpp v120, v120, v120 row_ror:1 row_mask:0xf bank_mask:0xf
	v_max_f32_dpp v130, v130, v130 row_ror:1 row_mask:0xf bank_mask:0xf
	v_cmp_eq_f32_e32 vcc, v116, v120
	v_cmp_eq_f32_e64 s[10:11], v126, v130
	s_sub_u32 s0, vcc_lo, s20
	s_subb_u32 s1, vcc_hi, s20
	s_andn2_b64 exec, vcc, s[0:1]
	ds_write_b64 v123, v[116:117] offset:40
	v_add_u32_e32 v117, 4, v117
	v_add_u32_e32 v121, v122, v117
	ds_read_b32 v115, v121 offset:4096
	s_sub_u32 s0, s10, s20
	s_subb_u32 s1, s11, s20
	s_andn2_b64 exec, s[10:11], s[0:1]
	ds_write_b64 v123, v[126:127] offset:4136
	v_add_u32_e32 v127, 4, v127
	v_add_u32_e32 v131, v122, v127
	ds_read_b32 v125, v131 offset:6144
	s_mov_b64 exec, -1
	s_waitcnt lgkmcnt(0)
	v_add_f32_e32 v118, v114, v115
	v_add_f32_e32 v128, v124, v125
	v_cmp_lt_u32_e32 vcc, v117, v119
	v_cmp_lt_u32_e64 s[10:11], v127, v119
	s_nop 0
	v_cndmask_b32_e32 v116, v112, v118, vcc
	v_cndmask_b32_e64 v126, v112, v128, s[10:11]
	s_nop 0
	v_max_f32_dpp v120, v116, v116 row_ror:8 row_mask:0xf bank_mask:0xf
	v_max_f32_dpp v130, v126, v126 row_ror:8 row_mask:0xf bank_mask:0xf
	s_nop 0
	v_max_f32_dpp v120, v120, v120 row_ror:4 row_mask:0xf bank_mask:0xf
	v_max_f32_dpp v130, v130, v130 row_ror:4 row_mask:0xf bank_mask:0xf
	s_nop 0
	v_max_f32_dpp v120, v120, v120 row_ror:2 row_mask:0xf bank_mask:0xf
	v_max_f32_dpp v130, v130, v130 row_ror:2 row_mask:0xf bank_mask:0xf
	s_nop 0
	v_max_f32_dpp v120, v120, v120 row_ror:1 row_mask:0xf bank_mask:0xf
	v_max_f32_dpp v130, v130, v130 row_ror:1 row_mask:0xf bank_mask:0xf
	v_cmp_eq_f32_e32 vcc, v116, v120
	v_cmp_eq_f32_e64 s[10:11], v126, v130
	s_sub_u32 s0, vcc_lo, s20
	s_subb_u32 s1, vcc_hi, s20
	s_andn2_b64 exec, vcc, s[0:1]
	ds_write_b64 v123, v[116:117] offset:48
	v_add_u32_e32 v117, 4, v117
	v_add_u32_e32 v121, v122, v117
	ds_read_b32 v115, v121 offset:4096
	s_sub_u32 s0, s10, s20
	s_subb_u32 s1, s11, s20
	s_andn2_b64 exec, s[10:11], s[0:1]
	ds_write_b64 v123, v[126:127] offset:4144
	v_add_u32_e32 v127, 4, v127
	v_add_u32_e32 v131, v122, v127
	ds_read_b32 v125, v131 offset:6144
	s_mov_b64 exec, -1
	s_waitcnt lgkmcnt(0)
	v_add_f32_e32 v118, v114, v115
	v_add_f32_e32 v128, v124, v125
	v_cmp_lt_u32_e32 vcc, v117, v119
	v_cmp_lt_u32_e64 s[10:11], v127, v119
	s_nop 0
	v_cndmask_b32_e32 v116, v112, v118, vcc
	v_cndmask_b32_e64 v126, v112, v128, s[10:11]
	s_nop 0
	v_max_f32_dpp v120, v116, v116 row_ror:8 row_mask:0xf bank_mask:0xf
	v_max_f32_dpp v130, v126, v126 row_ror:8 row_mask:0xf bank_mask:0xf
	s_nop 0
	v_max_f32_dpp v120, v120, v120 row_ror:4 row_mask:0xf bank_mask:0xf
	v_max_f32_dpp v130, v130, v130 row_ror:4 row_mask:0xf bank_mask:0xf
	s_nop 0
	v_max_f32_dpp v120, v120, v120 row_ror:2 row_mask:0xf bank_mask:0xf
	v_max_f32_dpp v130, v130, v130 row_ror:2 row_mask:0xf bank_mask:0xf
	s_nop 0
	v_max_f32_dpp v120, v120, v120 row_ror:1 row_mask:0xf bank_mask:0xf
	v_max_f32_dpp v130, v130, v130 row_ror:1 row_mask:0xf bank_mask:0xf
	v_cmp_eq_f32_e32 vcc, v116, v120
	v_cmp_eq_f32_e64 s[10:11], v126, v130
	s_sub_u32 s0, vcc_lo, s20
	s_subb_u32 s1, vcc_hi, s20
	s_andn2_b64 exec, vcc, s[0:1]
	ds_write_b64 v123, v[116:117] offset:56
	v_add_u32_e32 v117, 4, v117
	v_add_u32_e32 v121, v122, v117
	ds_read_b32 v115, v121 offset:4096
	s_sub_u32 s0, s10, s20
	s_subb_u32 s1, s11, s20
	s_andn2_b64 exec, s[10:11], s[0:1]
	ds_write_b64 v123, v[126:127] offset:4152
	v_add_u32_e32 v127, 4, v127
	v_add_u32_e32 v131, v122, v127
	ds_read_b32 v125, v131 offset:6144
	s_mov_b64 exec, -1
	s_waitcnt lgkmcnt(0)
	v_add_f32_e32 v118, v114, v115
	v_add_f32_e32 v128, v124, v125
	v_cmp_lt_u32_e32 vcc, v117, v119
	v_cmp_lt_u32_e64 s[10:11], v127, v119
	s_nop 0
	v_cndmask_b32_e32 v116, v112, v118, vcc
	v_cndmask_b32_e64 v126, v112, v128, s[10:11]
	s_nop 0
	v_max_f32_dpp v120, v116, v116 row_ror:8 row_mask:0xf bank_mask:0xf
	v_max_f32_dpp v130, v126, v126 row_ror:8 row_mask:0xf bank_mask:0xf
	s_nop 0
	v_max_f32_dpp v120, v120, v120 row_ror:4 row_mask:0xf bank_mask:0xf
	v_max_f32_dpp v130, v130, v130 row_ror:4 row_mask:0xf bank_mask:0xf
	s_nop 0
	v_max_f32_dpp v120, v120, v120 row_ror:2 row_mask:0xf bank_mask:0xf
	v_max_f32_dpp v130, v130, v130 row_ror:2 row_mask:0xf bank_mask:0xf
	s_nop 0
	v_max_f32_dpp v120, v120, v120 row_ror:1 row_mask:0xf bank_mask:0xf
	v_max_f32_dpp v130, v130, v130 row_ror:1 row_mask:0xf bank_mask:0xf
	v_cmp_eq_f32_e32 vcc, v116, v120
	v_cmp_eq_f32_e64 s[10:11], v126, v130
	s_sub_u32 s0, vcc_lo, s20
	s_subb_u32 s1, vcc_hi, s20
	s_andn2_b64 exec, vcc, s[0:1]
	ds_write_b64 v123, v[116:117] offset:64
	v_add_u32_e32 v117, 4, v117
	v_add_u32_e32 v121, v122, v117
	ds_read_b32 v115, v121 offset:4096
	s_sub_u32 s0, s10, s20
	s_subb_u32 s1, s11, s20
	s_andn2_b64 exec, s[10:11], s[0:1]
	ds_write_b64 v123, v[126:127] offset:4160
	v_add_u32_e32 v127, 4, v127
	v_add_u32_e32 v131, v122, v127
	ds_read_b32 v125, v131 offset:6144
	s_mov_b64 exec, -1
	s_waitcnt lgkmcnt(0)
; __device__ __forceinline__ void peer_score_unit(const Frame& F, int l, int unit) {
;     ...
; #pragma unroll
;         for (int k = 0; k < 16; ++k) {
;             float best = c[0]; int bi = 0;
; #pragma unroll
;             for (int i = 1; i < 16; ++i) if (c[i] > best) { best = c[i]; bi = i; }
;             int pj = 0, lim = 16;
; #pragma unroll
;             for (int i = 0; i < 16; ++i) { pj = (i == bi) ? p[i] : pj; lim = (i == bi) ? 16 / (i + 1) : lim; }
;             fv[k] = best; fi[k] = bi * 16 + pj;
;             const int np = pj + 1; const float nb = bl[np & 15];
; #pragma unroll
;             for (int i = 0; i < 16; ++i) if (i == bi) { p[i] = np; c[i] = (np < lim) ? a[i] + nb : -INFINITY; }
	v_add_f32_e32 v118, v114, v115
	v_add_f32_e32 v128, v124, v125
	v_cmp_lt_u32_e32 vcc, v117, v119
	v_cmp_lt_u32_e64 s[10:11], v127, v119
	s_nop 0
	v_cndmask_b32_e32 v116, v112, v118, vcc
	v_cndmask_b32_e64 v126, v112, v128, s[10:11]
	s_nop 0
	v_max_f32_dpp v120, v116, v116 row_ror:8 row_mask:0xf bank_mask:0xf
	v_max_f32_dpp v130, v126, v126 row_ror:8 row_mask:0xf bank_mask:0xf
	s_nop 0
	v_max_f32_dpp v120, v120, v120 row_ror:4 row_mask:0xf bank_mask:0xf
	v_max_f32_dpp v130, v130, v130 row_ror:4 row_mask:0xf bank_mask:0xf
	s_nop 0
	v_max_f32_dpp v120, v120, v120 row_ror:2 row_mask:0xf bank_mask:0xf
	v_max_f32_dpp v130, v130, v130 row_ror:2 row_mask:0xf bank_mask:0xf
	s_nop 0
	v_max_f32_dpp v120, v120, v120 row_ror:1 row_mask:0xf bank_mask:0xf
	v_max_f32_dpp v130, v130, v130 row_ror:1 row_mask:0xf bank_mask:0xf
	v_cmp_eq_f32_e32 vcc, v116, v120
	v_cmp_eq_f32_e64 s[10:11], v126, v130
	s_sub_u32 s0, vcc_lo, s20
	s_subb_u32 s1, vcc_hi, s20
	s_andn2_b64 exec, vcc, s[0:1]
	ds_write_b64 v123, v[116:117] offset:72
	v_add_u32_e32 v117, 4, v117
	v_add_u32_e32 v121, v122, v117
	ds_read_b32 v115, v121 offset:4096
	s_sub_u32 s0, s10, s20
	s_subb_u32 s1, s11, s20
	s_andn2_b64 exec, s[10:11], s[0:1]
	ds_write_b64 v123, v[126:127] offset:4168
	v_add_u32_e32 v127, 4, v127
	v_add_u32_e32 v131, v122, v127
	ds_read_b32 v125, v131 offset:6144
	s_mov_b64 exec, -1
	s_waitcnt lgkmcnt(0)
	v_add_f32_e32 v118, v114, v115
	v_add_f32_e32 v128, v124, v125
	v_cmp_lt_u32_e32 vcc, v117, v119
	v_cmp_lt_u32_e64 s[10:11], v127, v119
	s_nop 0
	v_cndmask_b32_e32 v116, v112, v118, vcc
	v_cndmask_b32_e64 v126, v112, v128, s[10:11]
	s_nop 0
	v_max_f32_dpp v120, v116, v116 row_ror:8 row_mask:0xf bank_mask:0xf
	v_max_f32_dpp v130, v126, v126 row_ror:8 row_mask:0xf bank_mask:0xf
	s_nop 0
	v_max_f32_dpp v120, v120, v120 row_ror:4 row_mask:0xf bank_mask:0xf
	v_max_f32_dpp v130, v130, v130 row_ror:4 row_mask:0xf bank_mask:0xf
	s_nop 0
	v_max_f32_dpp v120, v120, v120 row_ror:2 row_mask:0xf bank_mask:0xf
	v_max_f32_dpp v130, v130, v130 row_ror:2 row_mask:0xf bank_mask:0xf
	s_nop 0
	v_max_f32_dpp v120, v120, v120 row_ror:1 row_mask:0xf bank_mask:0xf
	v_max_f32_dpp v130, v130, v130 row_ror:1 row_mask:0xf bank_mask:0xf
	v_cmp_eq_f32_e32 vcc, v116, v120
	v_cmp_eq_f32_e64 s[10:11], v126, v130
	s_sub_u32 s0, vcc_lo, s20
	s_subb_u32 s1, vcc_hi, s20
	s_andn2_b64 exec, vcc, s[0:1]
	ds_write_b64 v123, v[116:117] offset:80
	v_add_u32_e32 v117, 4, v117
	v_add_u32_e32 v121, v122, v117
	ds_read_b32 v115, v121 offset:4096
	s_sub_u32 s0, s10, s20
	s_subb_u32 s1, s11, s20
	s_andn2_b64 exec, s[10:11], s[0:1]
	ds_write_b64 v123, v[126:127] offset:4176
	v_add_u32_e32 v127, 4, v127
	v_add_u32_e32 v131, v122, v127
	ds_read_b32 v125, v131 offset:6144
	s_mov_b64 exec, -1
	s_waitcnt lgkmcnt(0)
	v_add_f32_e32 v118, v114, v115
	v_add_f32_e32 v128, v124, v125
	v_cmp_lt_u32_e32 vcc, v117, v119
	v_cmp_lt_u32_e64 s[10:11], v127, v119
	s_nop 0
	v_cndmask_b32_e32 v116, v112, v118, vcc
	v_cndmask_b32_e64 v126, v112, v128, s[10:11]
	s_nop 0
	v_max_f32_dpp v120, v116, v116 row_ror:8 row_mask:0xf bank_mask:0xf
	v_max_f32_dpp v130, v126, v126 row_ror:8 row_mask:0xf bank_mask:0xf
	s_nop 0
	v_max_f32_dpp v120, v120, v120 row_ror:4 row_mask:0xf bank_mask:0xf
	v_max_f32_dpp v130, v130, v130 row_ror:4 row_mask:0xf bank_mask:0xf
	s_nop 0
	v_max_f32_dpp v120, v120, v120 row_ror:2 row_mask:0xf bank_mask:0xf
	v_max_f32_dpp v130, v130, v130 row_ror:2 row_mask:0xf bank_mask:0xf
	s_nop 0
	v_max_f32_dpp v120, v120, v120 row_ror:1 row_mask:0xf bank_mask:0xf
	v_max_f32_dpp v130, v130, v130 row_ror:1 row_mask:0xf bank_mask:0xf
	v_cmp_eq_f32_e32 vcc, v116, v120
	v_cmp_eq_f32_e64 s[10:11], v126, v130
	s_sub_u32 s0, vcc_lo, s20
	s_subb_u32 s1, vcc_hi, s20
	s_andn2_b64 exec, vcc, s[0:1]
	ds_write_b64 v123, v[116:117] offset:88
	v_add_u32_e32 v117, 4, v117
	v_add_u32_e32 v121, v122, v117
	ds_read_b32 v115, v121 offset:4096
	s_sub_u32 s0, s10, s20
	s_subb_u32 s1, s11, s20
	s_andn2_b64 exec, s[10:11], s[0:1]
	ds_write_b64 v123, v[126:127] offset:4184
	v_add_u32_e32 v127, 4, v127
	v_add_u32_e32 v131, v122, v127
	ds_read_b32 v125, v131 offset:6144
	s_mov_b64 exec, -1
	s_waitcnt lgkmcnt(0)
	v_add_f32_e32 v118, v114, v115
	v_add_f32_e32 v128, v124, v125
	v_cmp_lt_u32_e32 vcc, v117, v119
	v_cmp_lt_u32_e64 s[10:11], v127, v119
	s_nop 0
	v_cndmask_b32_e32 v116, v112, v118, vcc
	v_cndmask_b32_e64 v126, v112, v128, s[10:11]
	s_nop 0
	v_max_f32_dpp v120, v116, v116 row_ror:8 row_mask:0xf bank_mask:0xf
	v_max_f32_dpp v130, v126, v126 row_ror:8 row_mask:0xf bank_mask:0xf
	s_nop 0
	v_max_f32_dpp v120, v120, v120 row_ror:4 row_mask:0xf bank_mask:0xf
	v_max_f32_dpp v130, v130, v130 row_ror:4 row_mask:0xf bank_mask:0xf
	s_nop 0
	v_max_f32_dpp v120, v120, v120 row_ror:2 row_mask:0xf bank_mask:0xf
	v_max_f32_dpp v130, v130, v130 row_ror:2 row_mask:0xf bank_mask:0xf
	s_nop 0
	v_max_f32_dpp v120, v120, v120 row_ror:1 row_mask:0xf bank_mask:0xf
	v_max_f32_dpp v130, v130, v130 row_ror:1 row_mask:0xf bank_mask:0xf
	v_cmp_eq_f32_e32 vcc, v116, v120
	v_cmp_eq_f32_e64 s[10:11], v126, v130
	s_sub_u32 s0, vcc_lo, s20
	s_subb_u32 s1, vcc_hi, s20
	s_andn2_b64 exec, vcc, s[0:1]
	ds_write_b64 v123, v[116:117] offset:96
	v_add_u32_e32 v117, 4, v117
	v_add_u32_e32 v121, v122, v117
	ds_read_b32 v115, v121 offset:4096
	s_sub_u32 s0, s10, s20
	s_subb_u32 s1, s11, s20
	s_andn2_b64 exec, s[10:11], s[0:1]
	ds_write_b64 v123, v[126:127] offset:4192
	v_add_u32_e32 v127, 4, v127
	v_add_u32_e32 v131, v122, v127
	ds_read_b32 v125, v131 offset:6144
	s_mov_b64 exec, -1
	s_waitcnt lgkmcnt(0)
; __device__ __forceinline__ void peer_score_unit(const Frame& F, int l, int unit) {
;     ...
; #pragma unroll
;         for (int k = 0; k < 16; ++k) {
;             float best = c[0]; int bi = 0;
; #pragma unroll
;             for (int i = 1; i < 16; ++i) if (c[i] > best) { best = c[i]; bi = i; }
;             int pj = 0, lim = 16;
; #pragma unroll
;             for (int i = 0; i < 16; ++i) { pj = (i == bi) ? p[i] : pj; lim = (i == bi) ? 16 / (i + 1) : lim; }
;             fv[k] = best; fi[k] = bi * 16 + pj;
;             const int np = pj + 1; const float nb = bl[np & 15];
; #pragma unroll
;             for (int i = 0; i < 16; ++i) if (i == bi) { p[i] = np; c[i] = (np < lim) ? a[i] + nb : -INFINITY; }
;         }
;         float sum = 0.f;
;         const float fmx = fv[0];
; #pragma unroll
;         for (int k = 0; k < 16; ++k) { fv[k] = __expf(fv[k] - fmx); sum += fv[k]; }
;         const float inv = 1.0f / sum;
;         int* EID = (int*)(ws + WS_EID) + (size_t)(r0 + tid) * 128 + hd * 16; float* GW = (float*)(ws + WS_GW) + (size_t)(r0 + tid) * 128 + hd * 16;
; #pragma unroll
;         for (int k = 0; k < 16; ++k) { const int i1 = SI[tid * 16 + (fi[k] >> 4)], i2 = SI[(64 + tid) * 16 + (fi[k] & 15)]; EID[k] = i1 * 128 + i2; GW[k] = fv[k] * inv; }
	v_add_f32_e32 v118, v114, v115
	v_add_f32_e32 v128, v124, v125
	v_cmp_lt_u32_e32 vcc, v117, v119
	v_cmp_lt_u32_e64 s[10:11], v127, v119
	s_nop 0
	v_cndmask_b32_e32 v116, v112, v118, vcc
	v_cndmask_b32_e64 v126, v112, v128, s[10:11]
	s_nop 0
	v_max_f32_dpp v120, v116, v116 row_ror:8 row_mask:0xf bank_mask:0xf
	v_max_f32_dpp v130, v126, v126 row_ror:8 row_mask:0xf bank_mask:0xf
	s_nop 0
	v_max_f32_dpp v120, v120, v120 row_ror:4 row_mask:0xf bank_mask:0xf
	v_max_f32_dpp v130, v130, v130 row_ror:4 row_mask:0xf bank_mask:0xf
	s_nop 0
	v_max_f32_dpp v120, v120, v120 row_ror:2 row_mask:0xf bank_mask:0xf
	v_max_f32_dpp v130, v130, v130 row_ror:2 row_mask:0xf bank_mask:0xf
	s_nop 0
	v_max_f32_dpp v120, v120, v120 row_ror:1 row_mask:0xf bank_mask:0xf
	v_max_f32_dpp v130, v130, v130 row_ror:1 row_mask:0xf bank_mask:0xf
	v_cmp_eq_f32_e32 vcc, v116, v120
	v_cmp_eq_f32_e64 s[10:11], v126, v130
	s_sub_u32 s0, vcc_lo, s20
	s_subb_u32 s1, vcc_hi, s20
	s_andn2_b64 exec, vcc, s[0:1]
	ds_write_b64 v123, v[116:117] offset:104
	v_add_u32_e32 v117, 4, v117
	v_add_u32_e32 v121, v122, v117
	ds_read_b32 v115, v121 offset:4096
	s_sub_u32 s0, s10, s20
	s_subb_u32 s1, s11, s20
	s_andn2_b64 exec, s[10:11], s[0:1]
	ds_write_b64 v123, v[126:127] offset:4200
	v_add_u32_e32 v127, 4, v127
	v_add_u32_e32 v131, v122, v127
	ds_read_b32 v125, v131 offset:6144
	s_mov_b64 exec, -1
	s_waitcnt lgkmcnt(0)
	v_add_f32_e32 v118, v114, v115
	v_add_f32_e32 v128, v124, v125
	v_cmp_lt_u32_e32 vcc, v117, v119
	v_cmp_lt_u32_e64 s[10:11], v127, v119
	s_nop 0
	v_cndmask_b32_e32 v116, v112, v118, vcc
	v_cndmask_b32_e64 v126, v112, v128, s[10:11]
	s_nop 0
	v_max_f32_dpp v120, v116, v116 row_ror:8 row_mask:0xf bank_mask:0xf
	v_max_f32_dpp v130, v126, v126 row_ror:8 row_mask:0xf bank_mask:0xf
	s_nop 0
	v_max_f32_dpp v120, v120, v120 row_ror:4 row_mask:0xf bank_mask:0xf
	v_max_f32_dpp v130, v130, v130 row_ror:4 row_mask:0xf bank_mask:0xf
	s_nop 0
	v_max_f32_dpp v120, v120, v120 row_ror:2 row_mask:0xf bank_mask:0xf
	v_max_f32_dpp v130, v130, v130 row_ror:2 row_mask:0xf bank_mask:0xf
	s_nop 0
	v_max_f32_dpp v120, v120, v120 row_ror:1 row_mask:0xf bank_mask:0xf
	v_max_f32_dpp v130, v130, v130 row_ror:1 row_mask:0xf bank_mask:0xf
	v_cmp_eq_f32_e32 vcc, v116, v120
	v_cmp_eq_f32_e64 s[10:11], v126, v130
	s_sub_u32 s0, vcc_lo, s20
	s_subb_u32 s1, vcc_hi, s20
	s_andn2_b64 exec, vcc, s[0:1]
	ds_write_b64 v123, v[116:117] offset:112
	v_add_u32_e32 v117, 4, v117
	v_add_u32_e32 v121, v122, v117
	ds_read_b32 v115, v121 offset:4096
	s_sub_u32 s0, s10, s20
	s_subb_u32 s1, s11, s20
	s_andn2_b64 exec, s[10:11], s[0:1]
	ds_write_b64 v123, v[126:127] offset:4208
	v_add_u32_e32 v127, 4, v127
	v_add_u32_e32 v131, v122, v127
	ds_read_b32 v125, v131 offset:6144
	s_mov_b64 exec, -1
	s_waitcnt lgkmcnt(0)
	v_add_f32_e32 v118, v114, v115
	v_add_f32_e32 v128, v124, v125
	v_cmp_lt_u32_e32 vcc, v117, v119
	v_cmp_lt_u32_e64 s[10:11], v127, v119
	s_nop 0
	v_cndmask_b32_e32 v116, v112, v118, vcc
	v_cndmask_b32_e64 v126, v112, v128, s[10:11]
	s_nop 0
	v_max_f32_dpp v120, v116, v116 row_ror:8 row_mask:0xf bank_mask:0xf
	v_max_f32_dpp v130, v126, v126 row_ror:8 row_mask:0xf bank_mask:0xf
	s_nop 0
	v_max_f32_dpp v120, v120, v120 row_ror:4 row_mask:0xf bank_mask:0xf
	v_max_f32_dpp v130, v130, v130 row_ror:4 row_mask:0xf bank_mask:0xf
	s_nop 0
	v_max_f32_dpp v120, v120, v120 row_ror:2 row_mask:0xf bank_mask:0xf
	v_max_f32_dpp v130, v130, v130 row_ror:2 row_mask:0xf bank_mask:0xf
	s_nop 0
	v_max_f32_dpp v120, v120, v120 row_ror:1 row_mask:0xf bank_mask:0xf
	v_max_f32_dpp v130, v130, v130 row_ror:1 row_mask:0xf bank_mask:0xf
	v_cmp_eq_f32_e32 vcc, v116, v120
	v_cmp_eq_f32_e64 s[10:11], v126, v130
	s_sub_u32 s0, vcc_lo, s20
	s_subb_u32 s1, vcc_hi, s20
	s_andn2_b64 exec, vcc, s[0:1]
	ds_write_b64 v123, v[116:117] offset:120
	s_sub_u32 s0, s10, s20
	s_subb_u32 s1, s11, s20
	s_andn2_b64 exec, s[10:11], s[0:1]
	ds_write_b64 v123, v[126:127] offset:4216
	s_mov_b64 exec, -1
	ds_read_b64 v[114:115], v142
	ds_read_b64 v[124:125], v142 offset:4096
	v_lshrrev_b32_e32 v143, 4, v50
	v_lshlrev_b32_e32 v144, 2, v138
	v_lshl_add_u32 v143, v143, 9, v144
	v_add_u32_e32 v145, 0x4000, v143
	s_waitcnt lgkmcnt(0)
	v_lshrrev_b32_e32 v116, 8, v115
	v_and_b32_e32 v117, 0xff, v115
	v_lshl_add_u32 v116, v116, 2, v135
	v_add_u32_e32 v117, v135, v117
	ds_read_b32 v116, v116 offset:8192
	ds_read_b32 v117, v117 offset:12288
	v_sub_f32_e32 v114, v114, v136
	v_mul_f32_e32 v114, 0x3fb8aa3b, v114
	v_exp_f32_e32 v114, v114
	v_lshrrev_b32_e32 v126, 8, v125
	v_and_b32_e32 v127, 0xff, v125
	v_lshl_add_u32 v126, v126, 2, v135
	v_add_u32_e32 v127, v135, v127
	ds_read_b32 v126, v126 offset:10240
	ds_read_b32 v127, v127 offset:14336
	v_sub_f32_e32 v124, v124, v137
	v_mul_f32_e32 v124, 0x3fb8aa3b, v124
	v_exp_f32_e32 v124, v124
	s_nop 1
	v_add_f32_dpp v118, v114, v114 row_ror:8 row_mask:0xf bank_mask:0xf
	v_add_f32_dpp v128, v124, v124 row_ror:8 row_mask:0xf bank_mask:0xf
	s_nop 0
	v_add_f32_dpp v118, v118, v118 row_ror:4 row_mask:0xf bank_mask:0xf
	v_add_f32_dpp v128, v128, v128 row_ror:4 row_mask:0xf bank_mask:0xf
	s_nop 0
	v_add_f32_dpp v118, v118, v118 row_ror:2 row_mask:0xf bank_mask:0xf
	v_add_f32_dpp v128, v128, v128 row_ror:2 row_mask:0xf bank_mask:0xf
	s_nop 0
	v_add_f32_dpp v118, v118, v118 row_ror:1 row_mask:0xf bank_mask:0xf
	v_add_f32_dpp v128, v128, v128 row_ror:1 row_mask:0xf bank_mask:0xf
	v_div_scale_f32 v146, s[0:1], v118, v118, 1.0
	v_rcp_f32_e32 v147, v146
	s_nop 0
	v_fma_f32 v148, -v146, v147, 1.0
	v_fmac_f32_e32 v147, v148, v147
	v_div_scale_f32 v148, vcc, 1.0, v118, 1.0
	v_mul_f32_e32 v149, v148, v147
	v_fma_f32 v150, -v146, v149, v148
	v_fmac_f32_e32 v149, v150, v147
	v_fma_f32 v146, -v146, v149, v148
	v_div_fmas_f32 v146, v146, v147, v149
	v_div_fixup_f32 v146, v146, v118, 1.0
	v_div_scale_f32 v152, s[0:1], v128, v128, 1.0
	v_rcp_f32_e32 v153, v152
	s_nop 0
	v_fma_f32 v154, -v152, v153, 1.0
	v_fmac_f32_e32 v153, v154, v153
	v_div_scale_f32 v154, vcc, 1.0, v128, 1.0
	v_mul_f32_e32 v155, v154, v153
	v_fma_f32 v156, -v152, v155, v154
	v_fmac_f32_e32 v155, v156, v153
	v_fma_f32 v152, -v152, v155, v154
	v_div_fmas_f32 v152, v152, v153, v155
	v_div_fixup_f32 v152, v152, v128, 1.0
	v_mul_f32_e32 v114, v114, v146
	v_mul_f32_e32 v124, v124, v152
	s_waitcnt lgkmcnt(0)
	v_lshl_add_u32 v116, v116, 7, v117
	v_lshl_add_u32 v126, v126, 7, v127
	global_store_dword v143, v116, s[16:17]
	global_store_dword v143, v114, s[18:19]
	global_store_dword v145, v126, s[16:17]
	global_store_dword v145, v124, s[18:19]
; __device__ __forceinline__ void peer_score_unit(const Frame& F, int l, int unit) {
;     ...
;         const int cc = wave >> 2, nb = wave & 3, rl = lane & 31, h = lane >> 5;
;         const bf16_t* SK = (const bf16_t*)(ws + WS_SK) + ((size_t)((l * 8 + hd) * 2 + cc) * 128 + 32 * nb + rl) * 128 + 8 * h;
;         bf16x8 bfr[8];
; #pragma unroll
;         for (int ks = 0; ks < 8; ++ks) bfr[ks] = *(const bf16x8*)(SK + 16 * ks);
;         bf16x8 afr[2][8];
; #pragma unroll
;         for (int tb = 0; tb < 2; ++tb) { const bf16_t* QP = (const bf16_t*)(ws + WS_QP) + (size_t)(r0 + 32 * tb + rl) * D + hd * 256 + cc * 128 + 8 * h;
; #pragma unroll
;             for (int ks = 0; ks < 8; ++ks) afr[tb][ks] = *(const bf16x8*)(QP + 16 * ks); }
; template <unsigned MASK> __global__ void __launch_bounds__(NTHREADS, 2) fwd(Args A0) {
;     ...
;             { for (int u = q_block(F, cwb + 384); u < ((M / 64) * 8); u = q_block(F, cwb + 384)) { peer_score_unit(F, l, u); } }
.LBB0_2051:
	s_or_b64 exec, exec, s[52:53]
	s_andn2_b64 vcc, exec, s[44:45]
	s_barrier
	s_barrier
	s_cbranch_vccnz .LBB0_2046
	v_mov_b32_e32 v121, s87
	v_mov_b32_e32 v120, s101
	ds_write_b32 v121, v120
	s_branch .LBB0_2046
.Lp9_top_pf:
	s_and_b32 s6, s7, 7
	s_mov_b64 s[4:5], s[42:43]
	s_lshl_b32 s7, s7, 3
	s_andn2_b32 s7, s7, 63
	v_mov_b32_e32 v50, v49
	v_and_b32_e32 v6, 31, v48
	v_ashrrev_i32_e32 v7, 5, v48
	v_lshl_add_u32 v51, v7, 2, s55
	v_lshlrev_b32_e32 v112, 2, v6
	v_mul_lo_u32 v51, v51, s33
	v_add3_u32 v51, s56, v112, v51
	s_branch .Lp9_wait
